# K-loop LDS-DMA loads use SGPR-base+VGPR-offset addressing (no per-load 64-bit VALU add), B-fragment LDS base precomputed, NAT bias-table loads overlapped, merge-loop vmcnt counted
# speedup vs baseline: 1.0057x; 1.0057x over previous
.LBB0_303:
	s_add_u32 s41, s14, 0x10000
	s_addc_u32 s43, s15, 0
	s_add_u32 s12, s12, 0xc000
	v_mov_b32_e32 v2, 0
	s_addc_u32 s13, s13, 0
	s_mov_b32 s50, -2
	v_mov_b32_e32 v3, v2
	v_mov_b32_e32 v4, v2
	v_mov_b32_e32 v5, v2
	v_mov_b32_e32 v6, v2
	v_mov_b32_e32 v7, v2
	v_mov_b32_e32 v8, v2
	v_mov_b32_e32 v9, v2
	v_mov_b32_e32 v18, v2
	v_mov_b32_e32 v19, v2
	v_mov_b32_e32 v20, v2
	v_mov_b32_e32 v21, v2
	v_mov_b32_e32 v22, v2
	v_mov_b32_e32 v23, v2
	v_mov_b32_e32 v24, v2
	v_mov_b32_e32 v25, v2
	v_mov_b32_e32 v34, v2
	v_mov_b32_e32 v35, v2
	v_mov_b32_e32 v36, v2
	v_mov_b32_e32 v37, v2
	v_mov_b32_e32 v46, v2
	v_mov_b32_e32 v47, v2
	v_mov_b32_e32 v48, v2
	v_mov_b32_e32 v49, v2
	v_mov_b32_e32 v66, v2
	v_mov_b32_e32 v67, v2
	v_mov_b32_e32 v68, v2
	v_mov_b32_e32 v69, v2
	v_mov_b32_e32 v70, v2
	v_mov_b32_e32 v71, v2
	v_mov_b32_e32 v72, v2
	v_mov_b32_e32 v73, v2
	v_mov_b32_e32 v10, v2
	v_mov_b32_e32 v11, v2
	v_mov_b32_e32 v12, v2
	v_mov_b32_e32 v13, v2
	v_mov_b32_e32 v14, v2
	v_mov_b32_e32 v15, v2
	v_mov_b32_e32 v16, v2
	v_mov_b32_e32 v17, v2
	v_mov_b32_e32 v26, v2
	v_mov_b32_e32 v27, v2
	v_mov_b32_e32 v28, v2
	v_mov_b32_e32 v29, v2
	v_mov_b32_e32 v30, v2
	v_mov_b32_e32 v31, v2
	v_mov_b32_e32 v32, v2
	v_mov_b32_e32 v33, v2
	v_mov_b32_e32 v58, v2
	v_mov_b32_e32 v59, v2
	v_mov_b32_e32 v60, v2
	v_mov_b32_e32 v61, v2
	v_mov_b32_e32 v62, v2
	v_mov_b32_e32 v63, v2
	v_mov_b32_e32 v64, v2
	v_mov_b32_e32 v65, v2
	v_mov_b32_e32 v74, v2
	v_mov_b32_e32 v75, v2
	v_mov_b32_e32 v76, v2
	v_mov_b32_e32 v77, v2
	v_mov_b32_e32 v78, v2
	v_mov_b32_e32 v79, v2
	v_mov_b32_e32 v80, v2
	v_mov_b32_e32 v81, v2
	v_mov_b32_e32 v82, v2
	v_mov_b32_e32 v83, v2
	v_mov_b32_e32 v84, v2
	v_mov_b32_e32 v85, v2
	v_mov_b32_e32 v86, v2
	v_mov_b32_e32 v87, v2
	v_mov_b32_e32 v88, v2
	v_mov_b32_e32 v89, v2
	v_mov_b32_e32 v98, v2
	v_mov_b32_e32 v99, v2
	v_mov_b32_e32 v100, v2
	v_mov_b32_e32 v101, v2
	v_mov_b32_e32 v102, v2
	v_mov_b32_e32 v103, v2
	v_mov_b32_e32 v104, v2
	v_mov_b32_e32 v105, v2
	v_mov_b32_e32 v114, v2
	v_mov_b32_e32 v115, v2
	v_mov_b32_e32 v116, v2
	v_mov_b32_e32 v117, v2
	v_mov_b32_e32 v118, v2
	v_mov_b32_e32 v119, v2
	v_mov_b32_e32 v120, v2
	v_mov_b32_e32 v121, v2
	v_mov_b32_e32 v130, v2
	v_mov_b32_e32 v131, v2
	v_mov_b32_e32 v132, v2
	v_mov_b32_e32 v133, v2
	v_mov_b32_e32 v134, v2
	v_mov_b32_e32 v135, v2
	v_mov_b32_e32 v136, v2
	v_mov_b32_e32 v137, v2
	v_mov_b32_e32 v90, v2
	v_mov_b32_e32 v91, v2
	v_mov_b32_e32 v92, v2
	v_mov_b32_e32 v93, v2
	v_mov_b32_e32 v94, v2
	v_mov_b32_e32 v95, v2
	v_mov_b32_e32 v96, v2
	v_mov_b32_e32 v97, v2
	v_mov_b32_e32 v106, v2
	v_mov_b32_e32 v107, v2
	v_mov_b32_e32 v108, v2
	v_mov_b32_e32 v109, v2
	v_mov_b32_e32 v110, v2
	v_mov_b32_e32 v111, v2
	v_mov_b32_e32 v112, v2
	v_mov_b32_e32 v113, v2
	v_mov_b32_e32 v122, v2
	v_mov_b32_e32 v123, v2
	v_mov_b32_e32 v124, v2
	v_mov_b32_e32 v125, v2
	v_mov_b32_e32 v126, v2
	v_mov_b32_e32 v127, v2
	v_mov_b32_e32 v128, v2
	v_mov_b32_e32 v129, v2
	v_mov_b32_e32 v138, v2
	v_mov_b32_e32 v139, v2
	v_mov_b32_e32 v140, v2
	v_mov_b32_e32 v141, v2
	v_mov_b32_e32 v142, v2
	v_mov_b32_e32 v143, v2
	v_mov_b32_e32 v144, v2
	v_mov_b32_e32 v145, v2
	v_add_u32_e32 v229, 0x10000, v204
.LBB0_304:
	s_add_u32 s14, s12, 0x4000
	s_addc_u32 s15, s13, 0
	s_cmp_eq_u32 s50, 28
	s_cselect_b32 s22, s46, s14
	s_cselect_b32 s23, s47, s15
	s_cselect_b32 s16, s48, s41
	s_cselect_b32 s17, s49, s43
	s_add_u32 s14, s22, 0x8000
	s_addc_u32 s15, s23, 0
	s_add_i32 s51, 0, 0x10000
	s_add_i32 s54, 0, 0x14000
	ds_read_b128 v[38:41], v229
	ds_read_b128 v[42:45], v229 offset:1024
	ds_read_b128 v[50:53], v229 offset:2048
	ds_read_b128 v[54:57], v229 offset:3072
	ds_read_b128 v[146:149], v229 offset:16384
	ds_read_b128 v[150:153], v229 offset:17408
	ds_read_b128 v[166:169], v229 offset:18432
	ds_read_b128 v[170:173], v229 offset:19456
	s_add_i32 m0, s59, 0xc000
	ds_read_b128 v[174:177], v206
	ds_read_b128 v[178:181], v206 offset:1024
	ds_read_b128 v[182:185], v206 offset:2048
	ds_read_b128 v[186:189], v206 offset:3072
	ds_read_b128 v[190:193], v206 offset:4096
	ds_read_b128 v[194:197], v206 offset:5120
	ds_read_b128 v[198:201], v206 offset:6144
	ds_read_b128 v[212:215], v206 offset:7168
	global_load_lds_dwordx4 v154, s[12:13]
	s_add_i32 m0, s59, 0xe000
	s_nop 0
	global_load_lds_dwordx4 v156, s[12:13]
	s_waitcnt vmcnt(8)
	s_waitcnt lgkmcnt(0)
	s_barrier
	s_setprio 1
	s_waitcnt lgkmcnt(0)
	v_mfma_f32_16x16x32_bf16 v[142:145], v[38:41], v[174:177], v[142:145]
	v_mfma_f32_16x16x32_bf16 v[138:141], v[50:53], v[174:177], v[138:141]
	v_mfma_f32_16x16x32_bf16 v[126:129], v[38:41], v[182:185], v[126:129]
	v_mfma_f32_16x16x32_bf16 v[122:125], v[50:53], v[182:185], v[122:125]
	v_mfma_f32_16x16x32_bf16 v[110:113], v[38:41], v[190:193], v[110:113]
	v_mfma_f32_16x16x32_bf16 v[106:109], v[50:53], v[190:193], v[106:109]
	v_mfma_f32_16x16x32_bf16 v[94:97], v[38:41], v[198:201], v[94:97]
	v_mfma_f32_16x16x32_bf16 v[90:93], v[50:53], v[198:201], v[90:93]
	v_mfma_f32_16x16x32_bf16 v[142:145], v[42:45], v[178:181], v[142:145]
	v_mfma_f32_16x16x32_bf16 v[138:141], v[54:57], v[178:181], v[138:141]
	v_mfma_f32_16x16x32_bf16 v[126:129], v[42:45], v[186:189], v[126:129]
	v_mfma_f32_16x16x32_bf16 v[122:125], v[54:57], v[186:189], v[122:125]
	v_mfma_f32_16x16x32_bf16 v[110:113], v[42:45], v[194:197], v[110:113]
	v_mfma_f32_16x16x32_bf16 v[106:109], v[54:57], v[194:197], v[106:109]
	v_mfma_f32_16x16x32_bf16 v[94:97], v[42:45], v[212:215], v[94:97]
	v_mfma_f32_16x16x32_bf16 v[90:93], v[54:57], v[212:215], v[90:93]
	s_setprio 0
	s_setprio 1
	v_mfma_f32_16x16x32_bf16 v[134:137], v[146:149], v[174:177], v[134:137]
	v_mfma_f32_16x16x32_bf16 v[130:133], v[166:169], v[174:177], v[130:133]
	v_mfma_f32_16x16x32_bf16 v[118:121], v[146:149], v[182:185], v[118:121]
	v_mfma_f32_16x16x32_bf16 v[114:117], v[166:169], v[182:185], v[114:117]
	v_mfma_f32_16x16x32_bf16 v[102:105], v[146:149], v[190:193], v[102:105]
	v_mfma_f32_16x16x32_bf16 v[98:101], v[166:169], v[190:193], v[98:101]
	v_mfma_f32_16x16x32_bf16 v[86:89], v[146:149], v[198:201], v[86:89]
	v_mfma_f32_16x16x32_bf16 v[82:85], v[166:169], v[198:201], v[82:85]
	v_mfma_f32_16x16x32_bf16 v[134:137], v[150:153], v[178:181], v[134:137]
	v_mfma_f32_16x16x32_bf16 v[130:133], v[170:173], v[178:181], v[130:133]
	v_mfma_f32_16x16x32_bf16 v[118:121], v[150:153], v[186:189], v[118:121]
	v_mfma_f32_16x16x32_bf16 v[114:117], v[170:173], v[186:189], v[114:117]
	v_mfma_f32_16x16x32_bf16 v[102:105], v[150:153], v[194:197], v[102:105]
	v_mfma_f32_16x16x32_bf16 v[98:101], v[170:173], v[194:197], v[98:101]
	v_mfma_f32_16x16x32_bf16 v[86:89], v[150:153], v[212:215], v[86:89]
	v_mfma_f32_16x16x32_bf16 v[82:85], v[170:173], v[212:215], v[82:85]
	s_setprio 0
	s_barrier
	s_add_i32 s51, s51, s58
	s_mov_b32 m0, s51
	ds_read_b128 v[174:177], v206 offset:16384
	ds_read_b128 v[178:181], v206 offset:17408
	ds_read_b128 v[182:185], v206 offset:18432
	ds_read_b128 v[186:189], v206 offset:19456
	ds_read_b128 v[190:193], v206 offset:20480
	ds_read_b128 v[194:197], v206 offset:21504
	ds_read_b128 v[198:201], v206 offset:22528
	ds_read_b128 v[212:215], v206 offset:23552
	global_load_lds_dwordx4 v154, s[16:17]
	s_add_i32 m0, s51, 0x2000
	s_add_u32 s52, s16, 0x4000
	s_addc_u32 s53, s17, 0
	s_add_i32 s51, s54, s58
	global_load_lds_dwordx4 v156, s[16:17]
	s_mov_b32 m0, s51
	s_nop 0
	global_load_lds_dwordx4 v154, s[52:53]
	s_add_i32 m0, s51, 0x2000
	s_nop 0
	global_load_lds_dwordx4 v156, s[52:53]
	s_mov_b32 m0, s59
	s_nop 0
	global_load_lds_dwordx4 v154, s[22:23]
	s_mov_b32 m0, s60
	s_nop 0
	global_load_lds_dwordx4 v156, s[22:23]
	s_waitcnt vmcnt(8)
	s_waitcnt lgkmcnt(0)
	s_barrier
	s_setprio 1
	s_waitcnt lgkmcnt(0)
	v_mfma_f32_16x16x32_bf16 v[78:81], v[38:41], v[174:177], v[78:81]
	v_mfma_f32_16x16x32_bf16 v[74:77], v[50:53], v[174:177], v[74:77]
	v_mfma_f32_16x16x32_bf16 v[62:65], v[38:41], v[182:185], v[62:65]
	v_mfma_f32_16x16x32_bf16 v[58:61], v[50:53], v[182:185], v[58:61]
	v_mfma_f32_16x16x32_bf16 v[30:33], v[38:41], v[190:193], v[30:33]
	v_mfma_f32_16x16x32_bf16 v[26:29], v[50:53], v[190:193], v[26:29]
	v_mfma_f32_16x16x32_bf16 v[14:17], v[38:41], v[198:201], v[14:17]
	v_mfma_f32_16x16x32_bf16 v[10:13], v[50:53], v[198:201], v[10:13]
	v_mfma_f32_16x16x32_bf16 v[78:81], v[42:45], v[178:181], v[78:81]
	v_mfma_f32_16x16x32_bf16 v[74:77], v[54:57], v[178:181], v[74:77]
	v_mfma_f32_16x16x32_bf16 v[62:65], v[42:45], v[186:189], v[62:65]
	v_mfma_f32_16x16x32_bf16 v[58:61], v[54:57], v[186:189], v[58:61]
	v_mfma_f32_16x16x32_bf16 v[30:33], v[42:45], v[194:197], v[30:33]
	v_mfma_f32_16x16x32_bf16 v[26:29], v[54:57], v[194:197], v[26:29]
	v_mfma_f32_16x16x32_bf16 v[14:17], v[42:45], v[212:215], v[14:17]
	v_mfma_f32_16x16x32_bf16 v[10:13], v[54:57], v[212:215], v[10:13]
	s_setprio 0
	s_setprio 1
	v_mfma_f32_16x16x32_bf16 v[46:49], v[146:149], v[182:185], v[46:49]
	v_mfma_f32_16x16x32_bf16 v[34:37], v[166:169], v[182:185], v[34:37]
	v_mfma_f32_16x16x32_bf16 v[22:25], v[146:149], v[190:193], v[22:25]
	v_mfma_f32_16x16x32_bf16 v[18:21], v[166:169], v[190:193], v[18:21]
	v_mfma_f32_16x16x32_bf16 v[6:9], v[146:149], v[198:201], v[6:9]
	v_mfma_f32_16x16x32_bf16 v[2:5], v[166:169], v[198:201], v[2:5]
	v_mfma_f32_16x16x32_bf16 v[38:41], v[146:149], v[174:177], v[70:73]
	v_mfma_f32_16x16x32_bf16 v[42:45], v[166:169], v[174:177], v[66:69]
	v_mfma_f32_16x16x32_bf16 v[46:49], v[150:153], v[186:189], v[46:49]
	v_mfma_f32_16x16x32_bf16 v[34:37], v[170:173], v[186:189], v[34:37]
	v_mfma_f32_16x16x32_bf16 v[22:25], v[150:153], v[194:197], v[22:25]
	v_mfma_f32_16x16x32_bf16 v[18:21], v[170:173], v[194:197], v[18:21]
	v_mfma_f32_16x16x32_bf16 v[6:9], v[150:153], v[212:215], v[6:9]
	v_mfma_f32_16x16x32_bf16 v[2:5], v[170:173], v[212:215], v[2:5]
	v_mfma_f32_16x16x32_bf16 v[38:41], v[150:153], v[178:181], v[38:41]
	v_mfma_f32_16x16x32_bf16 v[42:45], v[170:173], v[178:181], v[42:45]
	s_setprio 0
	s_barrier
	s_add_i32 s51, 0, 0x18000
	s_add_i32 s52, 0, 0x1c000
	ds_read_b128 v[50:53], v229 offset:32768
	ds_read_b128 v[54:57], v229 offset:33792
	ds_read_b128 v[66:69], v229 offset:34816
	ds_read_b128 v[70:73], v229 offset:35840
	ds_read_b128 v[146:149], v229 offset:49152
	ds_read_b128 v[150:153], v229 offset:50176
	ds_read_b128 v[166:169], v229 offset:51200
	ds_read_b128 v[170:173], v229 offset:52224
	s_add_u32 s22, s22, 0x4000
	s_addc_u32 s23, s23, 0
	s_mov_b32 m0, s61
	ds_read_b128 v[174:177], v206 offset:32768
	ds_read_b128 v[178:181], v206 offset:33792
	ds_read_b128 v[182:185], v206 offset:34816
	ds_read_b128 v[186:189], v206 offset:35840
	ds_read_b128 v[190:193], v206 offset:36864
	ds_read_b128 v[194:197], v206 offset:37888
	ds_read_b128 v[198:201], v206 offset:38912
	ds_read_b128 v[212:215], v206 offset:39936
	global_load_lds_dwordx4 v154, s[22:23]
	s_mov_b32 m0, s62
	s_nop 0
	global_load_lds_dwordx4 v156, s[22:23]
	s_waitcnt vmcnt(8)
	s_waitcnt lgkmcnt(0)
	s_barrier
	s_setprio 1
	s_waitcnt lgkmcnt(0)
	v_mfma_f32_16x16x32_bf16 v[142:145], v[50:53], v[174:177], v[142:145]
	v_mfma_f32_16x16x32_bf16 v[138:141], v[66:69], v[174:177], v[138:141]
	v_mfma_f32_16x16x32_bf16 v[126:129], v[50:53], v[182:185], v[126:129]
	v_mfma_f32_16x16x32_bf16 v[122:125], v[66:69], v[182:185], v[122:125]
	v_mfma_f32_16x16x32_bf16 v[110:113], v[50:53], v[190:193], v[110:113]
	v_mfma_f32_16x16x32_bf16 v[106:109], v[66:69], v[190:193], v[106:109]
	v_mfma_f32_16x16x32_bf16 v[94:97], v[50:53], v[198:201], v[94:97]
	v_mfma_f32_16x16x32_bf16 v[90:93], v[66:69], v[198:201], v[90:93]
	v_mfma_f32_16x16x32_bf16 v[142:145], v[54:57], v[178:181], v[142:145]
	v_mfma_f32_16x16x32_bf16 v[138:141], v[70:73], v[178:181], v[138:141]
	v_mfma_f32_16x16x32_bf16 v[126:129], v[54:57], v[186:189], v[126:129]
	v_mfma_f32_16x16x32_bf16 v[122:125], v[70:73], v[186:189], v[122:125]
	v_mfma_f32_16x16x32_bf16 v[110:113], v[54:57], v[194:197], v[110:113]
	v_mfma_f32_16x16x32_bf16 v[106:109], v[70:73], v[194:197], v[106:109]
	v_mfma_f32_16x16x32_bf16 v[94:97], v[54:57], v[212:215], v[94:97]
	v_mfma_f32_16x16x32_bf16 v[90:93], v[70:73], v[212:215], v[90:93]
	s_setprio 0
	s_setprio 1
	v_mfma_f32_16x16x32_bf16 v[134:137], v[146:149], v[174:177], v[134:137]
	v_mfma_f32_16x16x32_bf16 v[130:133], v[166:169], v[174:177], v[130:133]
	v_mfma_f32_16x16x32_bf16 v[118:121], v[146:149], v[182:185], v[118:121]
	v_mfma_f32_16x16x32_bf16 v[114:117], v[166:169], v[182:185], v[114:117]
	v_mfma_f32_16x16x32_bf16 v[102:105], v[146:149], v[190:193], v[102:105]
	v_mfma_f32_16x16x32_bf16 v[98:101], v[166:169], v[190:193], v[98:101]
	v_mfma_f32_16x16x32_bf16 v[86:89], v[146:149], v[198:201], v[86:89]
	v_mfma_f32_16x16x32_bf16 v[82:85], v[166:169], v[198:201], v[82:85]
	v_mfma_f32_16x16x32_bf16 v[134:137], v[150:153], v[178:181], v[134:137]
	v_mfma_f32_16x16x32_bf16 v[130:133], v[170:173], v[178:181], v[130:133]
	v_mfma_f32_16x16x32_bf16 v[118:121], v[150:153], v[186:189], v[118:121]
	v_mfma_f32_16x16x32_bf16 v[114:117], v[170:173], v[186:189], v[114:117]
	v_mfma_f32_16x16x32_bf16 v[102:105], v[150:153], v[194:197], v[102:105]
	v_mfma_f32_16x16x32_bf16 v[98:101], v[170:173], v[194:197], v[98:101]
	v_mfma_f32_16x16x32_bf16 v[86:89], v[150:153], v[212:215], v[86:89]
	v_mfma_f32_16x16x32_bf16 v[82:85], v[170:173], v[212:215], v[82:85]
	s_setprio 0
	s_barrier
	s_add_u32 s22, s16, 0x8000
	s_addc_u32 s23, s17, 0
	s_add_i32 s51, s51, s58
	s_mov_b32 m0, s51
	ds_read_b128 v[174:177], v206 offset:49152
	ds_read_b128 v[178:181], v206 offset:50176
	ds_read_b128 v[182:185], v206 offset:51200
	ds_read_b128 v[186:189], v206 offset:52224
	ds_read_b128 v[190:193], v206 offset:53248
	ds_read_b128 v[194:197], v206 offset:54272
	ds_read_b128 v[198:201], v206 offset:55296
	ds_read_b128 v[212:215], v206 offset:56320
	global_load_lds_dwordx4 v154, s[22:23]
	s_add_i32 m0, s51, 0x2000
	s_add_u32 s16, s16, 0xc000
	s_addc_u32 s17, s17, 0
	global_load_lds_dwordx4 v156, s[22:23]
	s_add_i32 s22, s52, s58
	s_mov_b32 m0, s22
	s_nop 0
	global_load_lds_dwordx4 v154, s[16:17]
	s_add_i32 m0, s22, 0x2000
	s_nop 0
	global_load_lds_dwordx4 v156, s[16:17]
	s_mov_b32 m0, s72
	s_nop 0
	global_load_lds_dwordx4 v154, s[14:15]
	s_mov_b32 m0, s73
	s_nop 0
	global_load_lds_dwordx4 v156, s[14:15]
	s_waitcnt vmcnt(8)
	s_waitcnt lgkmcnt(0)
	s_barrier
	s_setprio 1
	s_waitcnt lgkmcnt(0)
	v_mfma_f32_16x16x32_bf16 v[78:81], v[50:53], v[174:177], v[78:81]
	v_mfma_f32_16x16x32_bf16 v[74:77], v[66:69], v[174:177], v[74:77]
	v_mfma_f32_16x16x32_bf16 v[62:65], v[50:53], v[182:185], v[62:65]
	v_mfma_f32_16x16x32_bf16 v[58:61], v[66:69], v[182:185], v[58:61]
	v_mfma_f32_16x16x32_bf16 v[30:33], v[50:53], v[190:193], v[30:33]
	v_mfma_f32_16x16x32_bf16 v[26:29], v[66:69], v[190:193], v[26:29]
	v_mfma_f32_16x16x32_bf16 v[14:17], v[50:53], v[198:201], v[14:17]
	v_mfma_f32_16x16x32_bf16 v[10:13], v[66:69], v[198:201], v[10:13]
	v_mfma_f32_16x16x32_bf16 v[78:81], v[54:57], v[178:181], v[78:81]
	v_mfma_f32_16x16x32_bf16 v[74:77], v[70:73], v[178:181], v[74:77]
	v_mfma_f32_16x16x32_bf16 v[62:65], v[54:57], v[186:189], v[62:65]
	v_mfma_f32_16x16x32_bf16 v[58:61], v[70:73], v[186:189], v[58:61]
	v_mfma_f32_16x16x32_bf16 v[30:33], v[54:57], v[194:197], v[30:33]
	v_mfma_f32_16x16x32_bf16 v[26:29], v[70:73], v[194:197], v[26:29]
	v_mfma_f32_16x16x32_bf16 v[14:17], v[54:57], v[212:215], v[14:17]
	v_mfma_f32_16x16x32_bf16 v[10:13], v[70:73], v[212:215], v[10:13]
	s_setprio 0
	s_setprio 1
	v_mfma_f32_16x16x32_bf16 v[38:41], v[146:149], v[174:177], v[38:41]
	v_mfma_f32_16x16x32_bf16 v[70:73], v[150:153], v[178:181], v[38:41]
	v_mfma_f32_16x16x32_bf16 v[38:41], v[166:169], v[174:177], v[42:45]
	v_mfma_f32_16x16x32_bf16 v[66:69], v[170:173], v[178:181], v[38:41]
	v_mfma_f32_16x16x32_bf16 v[38:41], v[146:149], v[182:185], v[46:49]
	v_mfma_f32_16x16x32_bf16 v[34:37], v[166:169], v[182:185], v[34:37]
	v_mfma_f32_16x16x32_bf16 v[22:25], v[146:149], v[190:193], v[22:25]
	v_mfma_f32_16x16x32_bf16 v[18:21], v[166:169], v[190:193], v[18:21]
	v_mfma_f32_16x16x32_bf16 v[6:9], v[146:149], v[198:201], v[6:9]
	v_mfma_f32_16x16x32_bf16 v[2:5], v[166:169], v[198:201], v[2:5]
	v_mfma_f32_16x16x32_bf16 v[46:49], v[150:153], v[186:189], v[38:41]
	v_mfma_f32_16x16x32_bf16 v[34:37], v[170:173], v[186:189], v[34:37]
	v_mfma_f32_16x16x32_bf16 v[22:25], v[150:153], v[194:197], v[22:25]
	v_mfma_f32_16x16x32_bf16 v[18:21], v[170:173], v[194:197], v[18:21]
	v_mfma_f32_16x16x32_bf16 v[6:9], v[150:153], v[212:215], v[6:9]
	v_mfma_f32_16x16x32_bf16 v[2:5], v[170:173], v[212:215], v[2:5]
	s_setprio 0
	s_barrier
	s_add_i32 s50, s50, 2
	s_add_u32 s41, s41, 0x10000
	s_addc_u32 s43, s43, 0
	s_add_u32 s12, s12, 0x10000
	s_addc_u32 s13, s13, 0
	s_cmp_gt_u32 s50, 29
	s_cbranch_scc0 .LBB0_304
	s_and_b64 vcc, exec, s[26:27]
	s_cbranch_vccz .LBB0_307
	s_barrier

.LBB0_597:
	s_barrier
	v_mbcnt_lo_u32_b32 v0, -1, 0
	v_mbcnt_hi_u32_b32 v0, -1, v0
	s_load_dwordx2 s[2:3], s[2:3], 0x60
	v_readlane_b32 s4, v255, 16
	v_or_b32_e32 v2, s81, v0
	v_readlane_b32 s5, v255, 17
	v_readfirstlane_b32 s23, v2
	s_waitcnt lgkmcnt(0)
	s_add_u32 s12, s2, s4
	s_movk_i32 s2, 0xe88
	s_addc_u32 s13, s3, s5
	v_cmp_gt_i32_e32 vcc, s2, v2
	v_mov_b32_e32 v0, 0
	v_ashrrev_i32_e32 v3, 31, v2
	s_waitcnt vmcnt(0)
	v_mov_b32_e32 v16, 0
	v_mov_b32_e32 v100, 0
	v_mov_b32_e32 v101, 0
	v_mov_b32_e32 v102, 0
	v_mov_b32_e32 v103, 0
	v_mov_b32_e32 v104, 0
	v_mov_b32_e32 v105, 0
	v_mov_b32_e32 v106, 0
	v_mov_b32_e32 v107, 0
	s_and_saveexec_b64 s[2:3], vcc
	s_cbranch_execz .LBB0_599
	v_lshl_add_u64 v[4:5], v[2:3], 2, s[12:13]
	global_load_dword v100, v[4:5], off
.LBB0_599:
	s_or_b64 exec, exec, s[2:3]
	s_movk_i32 s2, 0xc88
	v_cmp_gt_i32_e64 s[2:3], s2, v2
	s_and_saveexec_b64 s[4:5], s[2:3]
	s_cbranch_execz .LBB0_601
	v_lshl_add_u64 v[4:5], v[2:3], 2, s[12:13]
	global_load_dword v101, v[4:5], off offset:2048
.LBB0_601:
	s_or_b64 exec, exec, s[4:5]
	s_movk_i32 s4, 0xa88
	v_add_u32_e32 v4, 0x400, v2
	v_cmp_gt_i32_e64 s[4:5], s4, v2
	v_mov_b32_e32 v3, 0
	v_mov_b32_e32 v5, 0
	s_and_saveexec_b64 s[6:7], s[4:5]
	s_cbranch_execz .LBB0_603
	v_ashrrev_i32_e32 v5, 31, v4
	v_lshl_add_u64 v[6:7], v[4:5], 2, s[12:13]
	global_load_dword v102, v[6:7], off
.LBB0_603:
	s_or_b64 exec, exec, s[6:7]
	s_movk_i32 s6, 0x888
	v_add_u32_e32 v6, 0x600, v2
	v_cmp_gt_i32_e64 s[6:7], s6, v2
	s_and_saveexec_b64 s[14:15], s[6:7]
	s_cbranch_execz .LBB0_605
	v_ashrrev_i32_e32 v7, 31, v6
	v_lshl_add_u64 v[8:9], v[6:7], 2, s[12:13]
	global_load_dword v103, v[8:9], off
.LBB0_605:
	s_or_b64 exec, exec, s[14:15]
	s_movk_i32 s14, 0x688
	v_add_u32_e32 v8, 0x800, v2
	v_cmp_gt_i32_e64 s[36:37], s14, v2
	v_mov_b32_e32 v7, 0
	v_mov_b32_e32 v9, 0
	s_and_saveexec_b64 s[14:15], s[36:37]
	s_cbranch_execz .LBB0_607
	v_ashrrev_i32_e32 v9, 31, v8
	v_lshl_add_u64 v[10:11], v[8:9], 2, s[12:13]
	global_load_dword v104, v[10:11], off
.LBB0_607:
	s_or_b64 exec, exec, s[14:15]
	s_movk_i32 s14, 0x488
	v_add_u32_e32 v10, 0xa00, v2
	v_cmp_gt_i32_e64 s[38:39], s14, v2
	s_and_saveexec_b64 s[14:15], s[38:39]
	s_cbranch_execz .LBB0_609
	v_ashrrev_i32_e32 v11, 31, v10
	v_lshl_add_u64 v[12:13], v[10:11], 2, s[12:13]
	global_load_dword v105, v[12:13], off
.LBB0_609:
	s_or_b64 exec, exec, s[14:15]
	s_movk_i32 s14, 0x288
	v_add_u32_e32 v12, 0xc00, v2
	v_cmp_gt_i32_e64 s[40:41], s14, v2
	v_mov_b32_e32 v11, 0
	v_mov_b32_e32 v13, 0
	s_and_saveexec_b64 s[14:15], s[40:41]
	s_cbranch_execz .LBB0_611
	v_ashrrev_i32_e32 v13, 31, v12
	v_lshl_add_u64 v[14:15], v[12:13], 2, s[12:13]
	global_load_dword v106, v[14:15], off
.LBB0_611:
	s_or_b64 exec, exec, s[14:15]
	s_movk_i32 s14, 0x88
	v_add_u32_e32 v14, 0xe00, v2
	v_cmp_gt_i32_e64 s[42:43], s14, v2
	s_and_saveexec_b64 s[14:15], s[42:43]
	s_cbranch_execz .LBB0_711
	v_ashrrev_i32_e32 v15, 31, v14
	v_lshl_add_u64 v[18:19], v[14:15], 2, s[12:13]
	global_load_dword v107, v[18:19], off
	s_or_b64 exec, exec, s[14:15]
	s_waitcnt vmcnt(0)
	v_mul_f32_e32 v16, 0x3fb8aa3b, v100
	v_mul_f32_e32 v0, 0x3fb8aa3b, v101
	v_mul_f32_e32 v5, 0x3fb8aa3b, v102
	v_mul_f32_e32 v3, 0x3fb8aa3b, v103
	v_mul_f32_e32 v9, 0x3fb8aa3b, v104
	v_mul_f32_e32 v7, 0x3fb8aa3b, v105
	v_mul_f32_e32 v13, 0x3fb8aa3b, v106
	v_mul_f32_e32 v11, 0x3fb8aa3b, v107
	v_lshl_add_u32 v2, v2, 2, 0
	s_and_saveexec_b64 s[12:13], vcc
	s_cbranch_execnz .LBB0_712

.LBB0_711:
	s_or_b64 exec, exec, s[14:15]
	s_waitcnt vmcnt(0)
	v_mul_f32_e32 v16, 0x3fb8aa3b, v100
	v_mul_f32_e32 v0, 0x3fb8aa3b, v101
	v_mul_f32_e32 v5, 0x3fb8aa3b, v102
	v_mul_f32_e32 v3, 0x3fb8aa3b, v103
	v_mul_f32_e32 v9, 0x3fb8aa3b, v104
	v_mul_f32_e32 v7, 0x3fb8aa3b, v105
	v_mul_f32_e32 v13, 0x3fb8aa3b, v106
	v_mul_f32_e32 v11, 0x3fb8aa3b, v107
	v_lshl_add_u32 v2, v2, 2, 0
	s_and_saveexec_b64 s[12:13], vcc
	s_cbranch_execz .LBB0_613

.LBB0_998:
	s_cmp_lt_u32 s65, 30
	s_cselect_b64 s[16:17], -1, 0
	s_and_b64 s[22:23], s[16:17], exec
	s_cselect_b32 s22, 2, 0xffffffe2
	s_cselect_b32 s37, s15, s39
	s_cselect_b32 s36, s14, s38
	s_add_i32 s22, s22, s65
	s_ashr_i32 s23, s22, 31
	s_lshl_b64 s[22:23], s[22:23], 15
	s_add_u32 s36, s36, s22
	s_addc_u32 s37, s37, s23
	s_and_b64 s[16:17], s[16:17], exec
	v_add_u32_e32 v0, s58, v224
	s_cselect_b32 s17, s25, s41
	s_cselect_b32 s16, s24, s40
	s_add_i32 s66, s58, 0
	ds_read_b128 v[146:149], v0
	ds_read_b128 v[150:153], v0 offset:1024
	ds_read_b128 v[154:157], v0 offset:2048
	ds_read_b128 v[158:161], v0 offset:3072
	v_add_u32_e32 v0, s66, v223
	ds_read_b128 v[130:133], v0 offset:16384
	ds_read_b128 v[134:137], v0 offset:17408
	ds_read_b128 v[138:141], v0 offset:18432
	ds_read_b128 v[142:145], v0 offset:19456
	s_add_i32 s66, s51, s66
	s_add_u32 s16, s16, s22
	s_addc_u32 s17, s17, s23
	s_add_i32 s22, s45, s57
	v_add_u32_e32 v0, s66, v222
	s_mov_b32 m0, s22
	ds_read_b128 v[186:189], v0 offset:32768
	ds_read_b128 v[190:193], v0 offset:33792
	ds_read_b128 v[178:181], v0 offset:34816
	ds_read_b128 v[182:185], v0 offset:35840
	ds_read_b128 v[170:173], v0 offset:36864
	ds_read_b128 v[174:177], v0 offset:37888
	ds_read_b128 v[162:165], v0 offset:38912
	ds_read_b128 v[166:169], v0 offset:39936
	global_load_lds_dwordx4 v194, s[16:17]
	s_add_i32 m0, s22, 0x2000
	s_nop 0
	global_load_lds_dwordx4 v196, s[16:17]
	s_add_u32 s16, s16, 0x4000
	s_addc_u32 s17, s17, 0
	s_add_i32 m0, s22, 0x4000
	s_nop 0
	global_load_lds_dwordx4 v194, s[16:17]
	s_add_i32 m0, s22, 0x6000
	s_nop 0
	global_load_lds_dwordx4 v196, s[16:17]
	s_add_i32 m0, s22, 0x8000
	s_nop 0
	global_load_lds_dwordx4 v194, s[36:37]
	s_add_i32 m0, s22, 0xa000
	s_and_b32 s22, s65, 7
	global_load_lds_dwordx4 v196, s[36:37]
	s_cmp_lg_u32 s22, 6
	s_cbranch_scc1 .LBB0_1035
	s_and_b32 s16, s65, 24
	s_add_i32 s16, s27, s16
	s_ashr_i32 s17, s16, 31
	s_lshl_b64 s[16:17], s[16:17], 16
	s_add_u32 s16, s31, s16
	s_addc_u32 s17, s64, s17
	s_add_u32 s16, s16, s53
	s_addc_u32 s17, s17, s54
	v_lshl_add_u64 v[208:209], s[16:17], 0, v[198:199]
	v_add_co_u32_e32 v210, vcc, s11, v208
	s_nop 1
	v_addc_co_u32_e32 v211, vcc, 0, v209, vcc
	v_add_co_u32_e32 v200, vcc, 0x3000, v208
	s_nop 1
	v_addc_co_u32_e32 v201, vcc, 0, v209, vcc
	v_add_co_u32_e32 v204, vcc, s29, v208
	s_nop 1
	v_addc_co_u32_e32 v205, vcc, 0, v209, vcc
	v_add_co_u32_e32 v212, vcc, 0x5000, v208
	s_nop 1
	v_addc_co_u32_e32 v213, vcc, 0, v209, vcc
	global_load_dwordx2 v[206:207], v[208:209], off nt
	global_load_dwordx2 v[202:203], v[200:201], off nt
	s_nop 0
	global_load_dwordx2 v[200:201], v[204:205], off nt
	s_nop 0
	global_load_dwordx2 v[204:205], v[212:213], off nt
	v_add_co_u32_e32 v212, vcc, 0x6000, v208
	s_nop 1
	v_addc_co_u32_e32 v213, vcc, 0, v209, vcc
	v_add_co_u32_e32 v208, vcc, 0x7000, v208
	s_nop 1
	v_addc_co_u32_e32 v209, vcc, 0, v209, vcc
	global_load_dwordx2 v[218:219], v[210:211], off offset:-4096 nt
	global_load_dwordx2 v[216:217], v[210:211], off nt
	s_nop 0
	global_load_dwordx2 v[212:213], v[212:213], off nt
	s_nop 0
	global_load_dwordx2 v[214:215], v[208:209], off nt
	s_cmp_lt_u32 s22, 6
	s_mov_b64 s[16:17], -1
	s_cbranch_scc1 .LBB0_1036

.LBB0_1002:
	s_waitcnt lgkmcnt(0)
	s_barrier
	s_setprio 1
	s_waitcnt lgkmcnt(0)
	v_mfma_f32_16x16x32_bf16 v[126:129], v[146:149], v[186:189], v[126:129]
	v_mfma_f32_16x16x32_bf16 v[122:125], v[154:157], v[186:189], v[122:125]
	v_mfma_f32_16x16x32_bf16 v[110:113], v[146:149], v[178:181], v[110:113]
	v_mfma_f32_16x16x32_bf16 v[106:109], v[154:157], v[178:181], v[106:109]
	v_mfma_f32_16x16x32_bf16 v[94:97], v[146:149], v[170:173], v[94:97]
	v_mfma_f32_16x16x32_bf16 v[90:93], v[154:157], v[170:173], v[90:93]
	v_mfma_f32_16x16x32_bf16 v[78:81], v[146:149], v[162:165], v[78:81]
	v_mfma_f32_16x16x32_bf16 v[74:77], v[154:157], v[162:165], v[74:77]
	v_mfma_f32_16x16x32_bf16 v[126:129], v[150:153], v[190:193], v[126:129]
	v_mfma_f32_16x16x32_bf16 v[122:125], v[158:161], v[190:193], v[122:125]
	v_mfma_f32_16x16x32_bf16 v[110:113], v[150:153], v[182:185], v[110:113]
	v_mfma_f32_16x16x32_bf16 v[106:109], v[158:161], v[182:185], v[106:109]
	v_mfma_f32_16x16x32_bf16 v[94:97], v[150:153], v[174:177], v[94:97]
	v_mfma_f32_16x16x32_bf16 v[90:93], v[158:161], v[174:177], v[90:93]
	v_mfma_f32_16x16x32_bf16 v[78:81], v[150:153], v[166:169], v[78:81]
	v_mfma_f32_16x16x32_bf16 v[74:77], v[158:161], v[166:169], v[74:77]
	s_setprio 0
	s_setprio 1
	v_mfma_f32_16x16x32_bf16 v[118:121], v[130:133], v[186:189], v[118:121]
	v_mfma_f32_16x16x32_bf16 v[114:117], v[138:141], v[186:189], v[114:117]
	v_mfma_f32_16x16x32_bf16 v[102:105], v[130:133], v[178:181], v[102:105]
	v_mfma_f32_16x16x32_bf16 v[98:101], v[138:141], v[178:181], v[98:101]
	v_mfma_f32_16x16x32_bf16 v[86:89], v[130:133], v[170:173], v[86:89]
	v_mfma_f32_16x16x32_bf16 v[82:85], v[138:141], v[170:173], v[82:85]
	v_mfma_f32_16x16x32_bf16 v[70:73], v[130:133], v[162:165], v[70:73]
	v_mfma_f32_16x16x32_bf16 v[66:69], v[138:141], v[162:165], v[66:69]
	v_mfma_f32_16x16x32_bf16 v[118:121], v[134:137], v[190:193], v[118:121]
	v_mfma_f32_16x16x32_bf16 v[114:117], v[142:145], v[190:193], v[114:117]
	v_mfma_f32_16x16x32_bf16 v[102:105], v[134:137], v[182:185], v[102:105]
	v_mfma_f32_16x16x32_bf16 v[98:101], v[142:145], v[182:185], v[98:101]
	v_mfma_f32_16x16x32_bf16 v[86:89], v[134:137], v[174:177], v[86:89]
	v_mfma_f32_16x16x32_bf16 v[82:85], v[142:145], v[174:177], v[82:85]
	v_mfma_f32_16x16x32_bf16 v[70:73], v[134:137], v[166:169], v[70:73]
	v_mfma_f32_16x16x32_bf16 v[66:69], v[142:145], v[166:169], v[66:69]
	s_setprio 0
	s_barrier
	s_cmp_lg_u32 s22, 7
	s_cbranch_scc1 .LBB0_997
	s_cmp_gt_u32 s65, 7
	s_waitcnt vmcnt(6)
	v_cvt_f32_ubyte3_e32 v131, v206
	v_cvt_f32_ubyte2_e32 v130, v206
	v_cvt_f32_ubyte1_e32 v133, v206
	v_cvt_f32_ubyte0_e32 v132, v206
	s_cselect_b64 s[16:17], -1, 0
	v_pk_mul_f32 v[134:135], v[132:133], s[20:21] op_sel_hi:[1,0]
	v_pk_mul_f32 v[136:137], v[130:131], s[20:21] op_sel_hi:[1,0]
	v_cvt_f32_ubyte1_e32 v133, v207
	v_cvt_f32_ubyte0_e32 v132, v207
	v_cvt_f32_ubyte3_e32 v131, v207
	v_cvt_f32_ubyte2_e32 v130, v207
	v_pk_mul_f32 v[130:131], v[130:131], s[20:21] op_sel_hi:[1,0]
	v_pk_mul_f32 v[132:133], v[132:133], s[20:21] op_sel_hi:[1,0]
	v_pk_mul_f32 v[128:129], v[136:137], v[128:129]
	v_pk_mul_f32 v[126:127], v[134:135], v[126:127]
	s_mov_b64 s[22:23], -1
	s_and_b64 vcc, exec, s[16:17]
	s_cbranch_vccz .LBB0_1005
	v_pk_add_f32 v[64:65], v[64:65], v[128:129]
	v_pk_add_f32 v[62:63], v[62:63], v[126:127]
	v_pk_fma_f32 v[60:61], v[130:131], v[124:125], v[60:61]
	v_pk_fma_f32 v[58:59], v[132:133], v[122:123], v[58:59]
	s_mov_b64 s[22:23], 0

.LBB0_1110:
	s_add_u32 s12, s12, 0xc000
	s_addc_u32 s13, s13, 0
	s_add_u32 s31, s14, 0x10000
	v_mov_b32_e32 v2, 0
	s_addc_u32 s41, s15, 0
	s_mov_b32 s66, -2
	v_mov_b32_e32 v3, v2
	v_mov_b32_e32 v4, v2
	v_mov_b32_e32 v5, v2
	v_mov_b32_e32 v6, v2
	v_mov_b32_e32 v7, v2
	v_mov_b32_e32 v8, v2
	v_mov_b32_e32 v9, v2
	v_mov_b32_e32 v18, v2
	v_mov_b32_e32 v19, v2
	v_mov_b32_e32 v20, v2
	v_mov_b32_e32 v21, v2
	v_mov_b32_e32 v22, v2
	v_mov_b32_e32 v23, v2
	v_mov_b32_e32 v24, v2
	v_mov_b32_e32 v25, v2
	v_mov_b32_e32 v34, v2
	v_mov_b32_e32 v35, v2
	v_mov_b32_e32 v36, v2
	v_mov_b32_e32 v37, v2
	v_mov_b32_e32 v38, v2
	v_mov_b32_e32 v39, v2
	v_mov_b32_e32 v40, v2
	v_mov_b32_e32 v41, v2
	v_mov_b32_e32 v82, v2
	v_mov_b32_e32 v83, v2
	v_mov_b32_e32 v84, v2
	v_mov_b32_e32 v85, v2
	v_mov_b32_e32 v86, v2
	v_mov_b32_e32 v87, v2
	v_mov_b32_e32 v88, v2
	v_mov_b32_e32 v89, v2
	v_mov_b32_e32 v10, v2
	v_mov_b32_e32 v11, v2
	v_mov_b32_e32 v12, v2
	v_mov_b32_e32 v13, v2
	v_mov_b32_e32 v14, v2
	v_mov_b32_e32 v15, v2
	v_mov_b32_e32 v16, v2
	v_mov_b32_e32 v17, v2
	v_mov_b32_e32 v26, v2
	v_mov_b32_e32 v27, v2
	v_mov_b32_e32 v28, v2
	v_mov_b32_e32 v29, v2
	v_mov_b32_e32 v30, v2
	v_mov_b32_e32 v31, v2
	v_mov_b32_e32 v32, v2
	v_mov_b32_e32 v33, v2
	v_mov_b32_e32 v58, v2
	v_mov_b32_e32 v59, v2
	v_mov_b32_e32 v60, v2
	v_mov_b32_e32 v61, v2
	v_mov_b32_e32 v62, v2
	v_mov_b32_e32 v63, v2
	v_mov_b32_e32 v64, v2
	v_mov_b32_e32 v65, v2
	v_mov_b32_e32 v90, v2
	v_mov_b32_e32 v91, v2
	v_mov_b32_e32 v92, v2
	v_mov_b32_e32 v93, v2
	v_mov_b32_e32 v94, v2
	v_mov_b32_e32 v95, v2
	v_mov_b32_e32 v96, v2
	v_mov_b32_e32 v97, v2
	v_mov_b32_e32 v98, v2
	v_mov_b32_e32 v99, v2
	v_mov_b32_e32 v100, v2
	v_mov_b32_e32 v101, v2
	v_mov_b32_e32 v102, v2
	v_mov_b32_e32 v103, v2
	v_mov_b32_e32 v104, v2
	v_mov_b32_e32 v105, v2
	v_mov_b32_e32 v114, v2
	v_mov_b32_e32 v115, v2
	v_mov_b32_e32 v116, v2
	v_mov_b32_e32 v117, v2
	v_mov_b32_e32 v118, v2
	v_mov_b32_e32 v119, v2
	v_mov_b32_e32 v120, v2
	v_mov_b32_e32 v121, v2
	v_mov_b32_e32 v130, v2
	v_mov_b32_e32 v131, v2
	v_mov_b32_e32 v132, v2
	v_mov_b32_e32 v133, v2
	v_mov_b32_e32 v134, v2
	v_mov_b32_e32 v135, v2
	v_mov_b32_e32 v136, v2
	v_mov_b32_e32 v137, v2
	v_mov_b32_e32 v146, v2
	v_mov_b32_e32 v147, v2
	v_mov_b32_e32 v148, v2
	v_mov_b32_e32 v149, v2
	v_mov_b32_e32 v150, v2
	v_mov_b32_e32 v151, v2
	v_mov_b32_e32 v152, v2
	v_mov_b32_e32 v153, v2
	v_mov_b32_e32 v106, v2
	v_mov_b32_e32 v107, v2
	v_mov_b32_e32 v108, v2
	v_mov_b32_e32 v109, v2
	v_mov_b32_e32 v110, v2
	v_mov_b32_e32 v111, v2
	v_mov_b32_e32 v112, v2
	v_mov_b32_e32 v113, v2
	v_mov_b32_e32 v122, v2
	v_mov_b32_e32 v123, v2
	v_mov_b32_e32 v124, v2
	v_mov_b32_e32 v125, v2
	v_mov_b32_e32 v126, v2
	v_mov_b32_e32 v127, v2
	v_mov_b32_e32 v128, v2
	v_mov_b32_e32 v129, v2
	v_mov_b32_e32 v138, v2
	v_mov_b32_e32 v139, v2
	v_mov_b32_e32 v140, v2
	v_mov_b32_e32 v141, v2
	v_mov_b32_e32 v142, v2
	v_mov_b32_e32 v143, v2
	v_mov_b32_e32 v144, v2
	v_mov_b32_e32 v145, v2
	v_mov_b32_e32 v154, v2
	v_mov_b32_e32 v155, v2
	v_mov_b32_e32 v156, v2
	v_mov_b32_e32 v157, v2
	v_mov_b32_e32 v158, v2
	v_mov_b32_e32 v159, v2
	v_mov_b32_e32 v160, v2
	v_mov_b32_e32 v161, v2
	v_add_u32_e32 v229, 0x10000, v204
.LBB0_1111:
	s_add_u32 s14, s12, 0x4000
	s_addc_u32 s15, s13, 0
	s_cmp_eq_u32 s66, 28
	s_cselect_b32 s22, s42, s14
	s_cselect_b32 s23, s43, s15
	s_cselect_b32 s16, s44, s31
	s_cselect_b32 s17, s45, s41
	s_add_u32 s14, s22, 0x8000
	s_addc_u32 s15, s23, 0
	s_add_i32 s67, 0, 0x10000
	s_add_i32 s70, 0, 0x14000
	ds_read_b128 v[42:45], v229
	ds_read_b128 v[46:49], v229 offset:1024
	ds_read_b128 v[50:53], v229 offset:2048
	ds_read_b128 v[54:57], v229 offset:3072
	ds_read_b128 v[66:69], v229 offset:16384
	ds_read_b128 v[70:73], v229 offset:17408
	ds_read_b128 v[74:77], v229 offset:18432
	ds_read_b128 v[78:81], v229 offset:19456
	s_add_i32 m0, s50, 0xc000
	ds_read_b128 v[162:165], v205
	ds_read_b128 v[166:169], v205 offset:1024
	ds_read_b128 v[170:173], v205 offset:2048
	ds_read_b128 v[174:177], v205 offset:3072
	ds_read_b128 v[178:181], v205 offset:4096
	ds_read_b128 v[182:185], v205 offset:5120
	ds_read_b128 v[192:195], v205 offset:6144
	ds_read_b128 v[196:199], v205 offset:7168
	global_load_lds_dwordx4 v186, s[12:13]
	s_add_i32 m0, s50, 0xe000
	s_nop 0
	global_load_lds_dwordx4 v188, s[12:13]
	s_waitcnt vmcnt(8)
	s_waitcnt lgkmcnt(0)
	s_barrier
	s_setprio 1
	s_waitcnt lgkmcnt(0)
	v_mfma_f32_16x16x32_bf16 v[158:161], v[42:45], v[162:165], v[158:161]
	v_mfma_f32_16x16x32_bf16 v[154:157], v[50:53], v[162:165], v[154:157]
	v_mfma_f32_16x16x32_bf16 v[142:145], v[42:45], v[170:173], v[142:145]
	v_mfma_f32_16x16x32_bf16 v[138:141], v[50:53], v[170:173], v[138:141]
	v_mfma_f32_16x16x32_bf16 v[126:129], v[42:45], v[178:181], v[126:129]
	v_mfma_f32_16x16x32_bf16 v[122:125], v[50:53], v[178:181], v[122:125]
	v_mfma_f32_16x16x32_bf16 v[110:113], v[42:45], v[192:195], v[110:113]
	v_mfma_f32_16x16x32_bf16 v[106:109], v[50:53], v[192:195], v[106:109]
	v_mfma_f32_16x16x32_bf16 v[158:161], v[46:49], v[166:169], v[158:161]
	v_mfma_f32_16x16x32_bf16 v[154:157], v[54:57], v[166:169], v[154:157]
	v_mfma_f32_16x16x32_bf16 v[142:145], v[46:49], v[174:177], v[142:145]
	v_mfma_f32_16x16x32_bf16 v[138:141], v[54:57], v[174:177], v[138:141]
	v_mfma_f32_16x16x32_bf16 v[126:129], v[46:49], v[182:185], v[126:129]
	v_mfma_f32_16x16x32_bf16 v[122:125], v[54:57], v[182:185], v[122:125]
	v_mfma_f32_16x16x32_bf16 v[110:113], v[46:49], v[196:199], v[110:113]
	v_mfma_f32_16x16x32_bf16 v[106:109], v[54:57], v[196:199], v[106:109]
	s_setprio 0
	s_setprio 1
	v_mfma_f32_16x16x32_bf16 v[150:153], v[66:69], v[162:165], v[150:153]
	v_mfma_f32_16x16x32_bf16 v[146:149], v[74:77], v[162:165], v[146:149]
	v_mfma_f32_16x16x32_bf16 v[134:137], v[66:69], v[170:173], v[134:137]
	v_mfma_f32_16x16x32_bf16 v[130:133], v[74:77], v[170:173], v[130:133]
	v_mfma_f32_16x16x32_bf16 v[118:121], v[66:69], v[178:181], v[118:121]
	v_mfma_f32_16x16x32_bf16 v[114:117], v[74:77], v[178:181], v[114:117]
	v_mfma_f32_16x16x32_bf16 v[102:105], v[66:69], v[192:195], v[102:105]
	v_mfma_f32_16x16x32_bf16 v[98:101], v[74:77], v[192:195], v[98:101]
	v_mfma_f32_16x16x32_bf16 v[150:153], v[70:73], v[166:169], v[150:153]
	v_mfma_f32_16x16x32_bf16 v[146:149], v[78:81], v[166:169], v[146:149]
	v_mfma_f32_16x16x32_bf16 v[134:137], v[70:73], v[174:177], v[134:137]
	v_mfma_f32_16x16x32_bf16 v[130:133], v[78:81], v[174:177], v[130:133]
	v_mfma_f32_16x16x32_bf16 v[118:121], v[70:73], v[182:185], v[118:121]
	v_mfma_f32_16x16x32_bf16 v[114:117], v[78:81], v[182:185], v[114:117]
	v_mfma_f32_16x16x32_bf16 v[102:105], v[70:73], v[196:199], v[102:105]
	v_mfma_f32_16x16x32_bf16 v[98:101], v[78:81], v[196:199], v[98:101]
	s_setprio 0
	s_barrier
	s_add_i32 s67, s67, s49
	s_mov_b32 m0, s67
	ds_read_b128 v[162:165], v205 offset:16384
	ds_read_b128 v[166:169], v205 offset:17408
	ds_read_b128 v[170:173], v205 offset:18432
	ds_read_b128 v[174:177], v205 offset:19456
	ds_read_b128 v[178:181], v205 offset:20480
	ds_read_b128 v[182:185], v205 offset:21504
	ds_read_b128 v[192:195], v205 offset:22528
	ds_read_b128 v[196:199], v205 offset:23552
	global_load_lds_dwordx4 v186, s[16:17]
	s_add_i32 m0, s67, 0x2000
	s_add_u32 s68, s16, 0x4000
	s_addc_u32 s69, s17, 0
	s_add_i32 s67, s70, s49
	global_load_lds_dwordx4 v188, s[16:17]
	s_mov_b32 m0, s67
	s_nop 0
	global_load_lds_dwordx4 v186, s[68:69]
	s_add_i32 m0, s67, 0x2000
	s_nop 0
	global_load_lds_dwordx4 v188, s[68:69]
	s_mov_b32 m0, s50
	s_nop 0
	global_load_lds_dwordx4 v186, s[22:23]
	s_mov_b32 m0, s51
	s_nop 0
	global_load_lds_dwordx4 v188, s[22:23]
	s_waitcnt vmcnt(8)
	s_waitcnt lgkmcnt(0)
	s_barrier
	s_setprio 1
	s_waitcnt lgkmcnt(0)
	v_mfma_f32_16x16x32_bf16 v[94:97], v[42:45], v[162:165], v[94:97]
	v_mfma_f32_16x16x32_bf16 v[90:93], v[50:53], v[162:165], v[90:93]
	v_mfma_f32_16x16x32_bf16 v[62:65], v[42:45], v[170:173], v[62:65]
	v_mfma_f32_16x16x32_bf16 v[58:61], v[50:53], v[170:173], v[58:61]
	v_mfma_f32_16x16x32_bf16 v[30:33], v[42:45], v[178:181], v[30:33]
	v_mfma_f32_16x16x32_bf16 v[26:29], v[50:53], v[178:181], v[26:29]
	v_mfma_f32_16x16x32_bf16 v[14:17], v[42:45], v[192:195], v[14:17]
	v_mfma_f32_16x16x32_bf16 v[10:13], v[50:53], v[192:195], v[10:13]
	v_mfma_f32_16x16x32_bf16 v[94:97], v[46:49], v[166:169], v[94:97]
	v_mfma_f32_16x16x32_bf16 v[90:93], v[54:57], v[166:169], v[90:93]
	v_mfma_f32_16x16x32_bf16 v[62:65], v[46:49], v[174:177], v[62:65]
	v_mfma_f32_16x16x32_bf16 v[58:61], v[54:57], v[174:177], v[58:61]
	v_mfma_f32_16x16x32_bf16 v[30:33], v[46:49], v[182:185], v[30:33]
	v_mfma_f32_16x16x32_bf16 v[26:29], v[54:57], v[182:185], v[26:29]
	v_mfma_f32_16x16x32_bf16 v[14:17], v[46:49], v[196:199], v[14:17]
	v_mfma_f32_16x16x32_bf16 v[10:13], v[54:57], v[196:199], v[10:13]
	s_setprio 0
	s_setprio 1
	v_mfma_f32_16x16x32_bf16 v[38:41], v[66:69], v[170:173], v[38:41]
	v_mfma_f32_16x16x32_bf16 v[34:37], v[74:77], v[170:173], v[34:37]
	v_mfma_f32_16x16x32_bf16 v[22:25], v[66:69], v[178:181], v[22:25]
	v_mfma_f32_16x16x32_bf16 v[18:21], v[74:77], v[178:181], v[18:21]
	v_mfma_f32_16x16x32_bf16 v[6:9], v[66:69], v[192:195], v[6:9]
	v_mfma_f32_16x16x32_bf16 v[2:5], v[74:77], v[192:195], v[2:5]
	v_mfma_f32_16x16x32_bf16 v[42:45], v[66:69], v[162:165], v[86:89]
	v_mfma_f32_16x16x32_bf16 v[46:49], v[74:77], v[162:165], v[82:85]
	v_mfma_f32_16x16x32_bf16 v[38:41], v[70:73], v[174:177], v[38:41]
	v_mfma_f32_16x16x32_bf16 v[34:37], v[78:81], v[174:177], v[34:37]
	v_mfma_f32_16x16x32_bf16 v[22:25], v[70:73], v[182:185], v[22:25]
	v_mfma_f32_16x16x32_bf16 v[18:21], v[78:81], v[182:185], v[18:21]
	v_mfma_f32_16x16x32_bf16 v[6:9], v[70:73], v[196:199], v[6:9]
	v_mfma_f32_16x16x32_bf16 v[2:5], v[78:81], v[196:199], v[2:5]
	v_mfma_f32_16x16x32_bf16 v[42:45], v[70:73], v[166:169], v[42:45]
	v_mfma_f32_16x16x32_bf16 v[46:49], v[78:81], v[166:169], v[46:49]
	s_setprio 0
	s_barrier
	s_add_i32 s67, 0, 0x18000
	s_add_i32 s68, 0, 0x1c000
	ds_read_b128 v[50:53], v229 offset:32768
	ds_read_b128 v[54:57], v229 offset:33792
	ds_read_b128 v[66:69], v229 offset:34816
	ds_read_b128 v[70:73], v229 offset:35840
	ds_read_b128 v[74:77], v229 offset:49152
	ds_read_b128 v[78:81], v229 offset:50176
	ds_read_b128 v[162:165], v229 offset:51200
	ds_read_b128 v[166:169], v229 offset:52224
	s_add_u32 s22, s22, 0x4000
	s_addc_u32 s23, s23, 0
	s_mov_b32 m0, s52
	ds_read_b128 v[82:85], v205 offset:32768
	ds_read_b128 v[86:89], v205 offset:33792
	ds_read_b128 v[170:173], v205 offset:34816
	ds_read_b128 v[174:177], v205 offset:35840
	ds_read_b128 v[178:181], v205 offset:36864
	ds_read_b128 v[182:185], v205 offset:37888
	ds_read_b128 v[192:195], v205 offset:38912
	ds_read_b128 v[196:199], v205 offset:39936
	global_load_lds_dwordx4 v186, s[22:23]
	s_mov_b32 m0, s53
	s_nop 0
	global_load_lds_dwordx4 v188, s[22:23]
	s_waitcnt vmcnt(8)
	s_waitcnt lgkmcnt(0)
	s_barrier
	s_setprio 1
	s_waitcnt lgkmcnt(0)
	v_mfma_f32_16x16x32_bf16 v[158:161], v[50:53], v[82:85], v[158:161]
	v_mfma_f32_16x16x32_bf16 v[154:157], v[66:69], v[82:85], v[154:157]
	v_mfma_f32_16x16x32_bf16 v[142:145], v[50:53], v[170:173], v[142:145]
	v_mfma_f32_16x16x32_bf16 v[138:141], v[66:69], v[170:173], v[138:141]
	v_mfma_f32_16x16x32_bf16 v[126:129], v[50:53], v[178:181], v[126:129]
	v_mfma_f32_16x16x32_bf16 v[122:125], v[66:69], v[178:181], v[122:125]
	v_mfma_f32_16x16x32_bf16 v[110:113], v[50:53], v[192:195], v[110:113]
	v_mfma_f32_16x16x32_bf16 v[106:109], v[66:69], v[192:195], v[106:109]
	v_mfma_f32_16x16x32_bf16 v[158:161], v[54:57], v[86:89], v[158:161]
	v_mfma_f32_16x16x32_bf16 v[154:157], v[70:73], v[86:89], v[154:157]
	v_mfma_f32_16x16x32_bf16 v[142:145], v[54:57], v[174:177], v[142:145]
	v_mfma_f32_16x16x32_bf16 v[138:141], v[70:73], v[174:177], v[138:141]
	v_mfma_f32_16x16x32_bf16 v[126:129], v[54:57], v[182:185], v[126:129]
	v_mfma_f32_16x16x32_bf16 v[122:125], v[70:73], v[182:185], v[122:125]
	v_mfma_f32_16x16x32_bf16 v[110:113], v[54:57], v[196:199], v[110:113]
	v_mfma_f32_16x16x32_bf16 v[106:109], v[70:73], v[196:199], v[106:109]
	s_setprio 0
	s_setprio 1
	v_mfma_f32_16x16x32_bf16 v[150:153], v[74:77], v[82:85], v[150:153]
	v_mfma_f32_16x16x32_bf16 v[82:85], v[162:165], v[82:85], v[146:149]
	v_mfma_f32_16x16x32_bf16 v[146:149], v[166:169], v[86:89], v[82:85]
	v_mfma_f32_16x16x32_bf16 v[82:85], v[74:77], v[170:173], v[134:137]
	v_mfma_f32_16x16x32_bf16 v[134:137], v[78:81], v[174:177], v[82:85]
	v_mfma_f32_16x16x32_bf16 v[82:85], v[162:165], v[170:173], v[130:133]
	v_mfma_f32_16x16x32_bf16 v[130:133], v[166:169], v[174:177], v[82:85]
	v_mfma_f32_16x16x32_bf16 v[82:85], v[74:77], v[178:181], v[118:121]
	v_mfma_f32_16x16x32_bf16 v[118:121], v[78:81], v[182:185], v[82:85]
	v_mfma_f32_16x16x32_bf16 v[82:85], v[162:165], v[178:181], v[114:117]
	v_mfma_f32_16x16x32_bf16 v[114:117], v[166:169], v[182:185], v[82:85]
	v_mfma_f32_16x16x32_bf16 v[82:85], v[74:77], v[192:195], v[102:105]
	v_mfma_f32_16x16x32_bf16 v[102:105], v[78:81], v[196:199], v[82:85]
	v_mfma_f32_16x16x32_bf16 v[82:85], v[162:165], v[192:195], v[98:101]
	v_mfma_f32_16x16x32_bf16 v[150:153], v[78:81], v[86:89], v[150:153]
	v_mfma_f32_16x16x32_bf16 v[98:101], v[166:169], v[196:199], v[82:85]
	s_setprio 0
	s_barrier
	s_add_u32 s22, s16, 0x8000
	s_addc_u32 s23, s17, 0
	s_add_i32 s67, s67, s49
	s_mov_b32 m0, s67
	ds_read_b128 v[82:85], v205 offset:49152
	ds_read_b128 v[170:173], v205 offset:50176
	ds_read_b128 v[174:177], v205 offset:51200
	ds_read_b128 v[178:181], v205 offset:52224
	ds_read_b128 v[182:185], v205 offset:53248
	ds_read_b128 v[192:195], v205 offset:54272
	ds_read_b128 v[196:199], v205 offset:55296
	ds_read_b128 v[212:215], v205 offset:56320
	global_load_lds_dwordx4 v186, s[22:23]
	s_add_i32 m0, s67, 0x2000
	s_add_u32 s16, s16, 0xc000
	s_addc_u32 s17, s17, 0
	global_load_lds_dwordx4 v188, s[22:23]
	s_add_i32 s22, s68, s49
	s_mov_b32 m0, s22
	s_nop 0
	global_load_lds_dwordx4 v186, s[16:17]
	s_add_i32 m0, s22, 0x2000
	s_nop 0
	global_load_lds_dwordx4 v188, s[16:17]
	s_mov_b32 m0, s60
	s_nop 0
	global_load_lds_dwordx4 v186, s[14:15]
	s_mov_b32 m0, s61
	s_nop 0
	global_load_lds_dwordx4 v188, s[14:15]
	s_waitcnt vmcnt(8)
	s_waitcnt lgkmcnt(0)
	s_barrier
	s_setprio 1
	s_waitcnt lgkmcnt(0)
	v_mfma_f32_16x16x32_bf16 v[86:89], v[50:53], v[82:85], v[94:97]
	v_mfma_f32_16x16x32_bf16 v[94:97], v[54:57], v[170:173], v[86:89]
	v_mfma_f32_16x16x32_bf16 v[86:89], v[66:69], v[82:85], v[90:93]
	v_mfma_f32_16x16x32_bf16 v[62:65], v[50:53], v[174:177], v[62:65]
	v_mfma_f32_16x16x32_bf16 v[58:61], v[66:69], v[174:177], v[58:61]
	v_mfma_f32_16x16x32_bf16 v[30:33], v[50:53], v[182:185], v[30:33]
	v_mfma_f32_16x16x32_bf16 v[26:29], v[66:69], v[182:185], v[26:29]
	v_mfma_f32_16x16x32_bf16 v[14:17], v[50:53], v[196:199], v[14:17]
	v_mfma_f32_16x16x32_bf16 v[10:13], v[66:69], v[196:199], v[10:13]
	v_mfma_f32_16x16x32_bf16 v[90:93], v[70:73], v[170:173], v[86:89]
	v_mfma_f32_16x16x32_bf16 v[62:65], v[54:57], v[178:181], v[62:65]
	v_mfma_f32_16x16x32_bf16 v[58:61], v[70:73], v[178:181], v[58:61]
	v_mfma_f32_16x16x32_bf16 v[30:33], v[54:57], v[192:195], v[30:33]
	v_mfma_f32_16x16x32_bf16 v[26:29], v[70:73], v[192:195], v[26:29]
	v_mfma_f32_16x16x32_bf16 v[14:17], v[54:57], v[212:215], v[14:17]
	v_mfma_f32_16x16x32_bf16 v[10:13], v[70:73], v[212:215], v[10:13]
	s_setprio 0
	s_setprio 1
	v_mfma_f32_16x16x32_bf16 v[42:45], v[74:77], v[82:85], v[42:45]
	v_mfma_f32_16x16x32_bf16 v[86:89], v[78:81], v[170:173], v[42:45]
	v_mfma_f32_16x16x32_bf16 v[42:45], v[162:165], v[82:85], v[46:49]
	v_mfma_f32_16x16x32_bf16 v[38:41], v[74:77], v[174:177], v[38:41]
	v_mfma_f32_16x16x32_bf16 v[34:37], v[162:165], v[174:177], v[34:37]
	v_mfma_f32_16x16x32_bf16 v[22:25], v[74:77], v[182:185], v[22:25]
	v_mfma_f32_16x16x32_bf16 v[18:21], v[162:165], v[182:185], v[18:21]
	v_mfma_f32_16x16x32_bf16 v[6:9], v[74:77], v[196:199], v[6:9]
	v_mfma_f32_16x16x32_bf16 v[2:5], v[162:165], v[196:199], v[2:5]
	v_mfma_f32_16x16x32_bf16 v[82:85], v[166:169], v[170:173], v[42:45]
	v_mfma_f32_16x16x32_bf16 v[38:41], v[78:81], v[178:181], v[38:41]
	v_mfma_f32_16x16x32_bf16 v[34:37], v[166:169], v[178:181], v[34:37]
	v_mfma_f32_16x16x32_bf16 v[22:25], v[78:81], v[192:195], v[22:25]
	v_mfma_f32_16x16x32_bf16 v[18:21], v[166:169], v[192:195], v[18:21]
	v_mfma_f32_16x16x32_bf16 v[6:9], v[78:81], v[212:215], v[6:9]
	v_mfma_f32_16x16x32_bf16 v[2:5], v[166:169], v[212:215], v[2:5]
	s_setprio 0
	s_barrier
	s_add_i32 s66, s66, 2
	s_add_u32 s12, s12, 0x10000
	s_addc_u32 s13, s13, 0
	s_add_u32 s31, s31, 0x10000
	s_addc_u32 s41, s41, 0
	s_cmp_gt_u32 s66, 29
	s_cbranch_scc0 .LBB0_1111
	s_and_b64 vcc, exec, s[24:25]
	s_cbranch_vccz .LBB0_1114
	s_barrier

.LBB0_1195:
	s_add_u32 s31, s12, s52
	s_addc_u32 s41, s13, 0
	s_add_u32 s73, s14, 0x10000
	v_mov_b32_e32 v2, 0
	s_addc_u32 s74, s15, 0
	s_mov_b64 s[14:15], 1
	v_mov_b32_e32 v3, v2
	v_mov_b32_e32 v4, v2
	v_mov_b32_e32 v5, v2
	v_mov_b32_e32 v6, v2
	v_mov_b32_e32 v7, v2
	v_mov_b32_e32 v8, v2
	v_mov_b32_e32 v9, v2
	v_mov_b32_e32 v18, v2
	v_mov_b32_e32 v19, v2
	v_mov_b32_e32 v20, v2
	v_mov_b32_e32 v21, v2
	v_mov_b32_e32 v22, v2
	v_mov_b32_e32 v23, v2
	v_mov_b32_e32 v24, v2
	v_mov_b32_e32 v25, v2
	v_mov_b32_e32 v34, v2
	v_mov_b32_e32 v35, v2
	v_mov_b32_e32 v36, v2
	v_mov_b32_e32 v37, v2
	v_mov_b32_e32 v38, v2
	v_mov_b32_e32 v39, v2
	v_mov_b32_e32 v40, v2
	v_mov_b32_e32 v41, v2
	v_mov_b32_e32 v50, v2
	v_mov_b32_e32 v51, v2
	v_mov_b32_e32 v52, v2
	v_mov_b32_e32 v53, v2
	v_mov_b32_e32 v54, v2
	v_mov_b32_e32 v55, v2
	v_mov_b32_e32 v56, v2
	v_mov_b32_e32 v57, v2
	v_mov_b32_e32 v10, v2
	v_mov_b32_e32 v11, v2
	v_mov_b32_e32 v12, v2
	v_mov_b32_e32 v13, v2
	v_mov_b32_e32 v14, v2
	v_mov_b32_e32 v15, v2
	v_mov_b32_e32 v16, v2
	v_mov_b32_e32 v17, v2
	v_mov_b32_e32 v26, v2
	v_mov_b32_e32 v27, v2
	v_mov_b32_e32 v28, v2
	v_mov_b32_e32 v29, v2
	v_mov_b32_e32 v30, v2
	v_mov_b32_e32 v31, v2
	v_mov_b32_e32 v32, v2
	v_mov_b32_e32 v33, v2
	v_mov_b32_e32 v42, v2
	v_mov_b32_e32 v43, v2
	v_mov_b32_e32 v44, v2
	v_mov_b32_e32 v45, v2
	v_mov_b32_e32 v46, v2
	v_mov_b32_e32 v47, v2
	v_mov_b32_e32 v48, v2
	v_mov_b32_e32 v49, v2
	v_mov_b32_e32 v58, v2
	v_mov_b32_e32 v59, v2
	v_mov_b32_e32 v60, v2
	v_mov_b32_e32 v61, v2
	v_mov_b32_e32 v62, v2
	v_mov_b32_e32 v63, v2
	v_mov_b32_e32 v64, v2
	v_mov_b32_e32 v65, v2
	v_mov_b32_e32 v82, v2
	v_mov_b32_e32 v83, v2
	v_mov_b32_e32 v84, v2
	v_mov_b32_e32 v85, v2
	v_mov_b32_e32 v86, v2
	v_mov_b32_e32 v87, v2
	v_mov_b32_e32 v88, v2
	v_mov_b32_e32 v89, v2
	v_mov_b32_e32 v98, v2
	v_mov_b32_e32 v99, v2
	v_mov_b32_e32 v100, v2
	v_mov_b32_e32 v101, v2
	v_mov_b32_e32 v102, v2
	v_mov_b32_e32 v103, v2
	v_mov_b32_e32 v104, v2
	v_mov_b32_e32 v105, v2
	v_mov_b32_e32 v114, v2
	v_mov_b32_e32 v115, v2
	v_mov_b32_e32 v116, v2
	v_mov_b32_e32 v117, v2
	v_mov_b32_e32 v118, v2
	v_mov_b32_e32 v119, v2
	v_mov_b32_e32 v120, v2
	v_mov_b32_e32 v121, v2
	v_mov_b32_e32 v130, v2
	v_mov_b32_e32 v131, v2
	v_mov_b32_e32 v132, v2
	v_mov_b32_e32 v133, v2
	v_mov_b32_e32 v134, v2
	v_mov_b32_e32 v135, v2
	v_mov_b32_e32 v136, v2
	v_mov_b32_e32 v137, v2
	v_mov_b32_e32 v90, v2
	v_mov_b32_e32 v91, v2
	v_mov_b32_e32 v92, v2
	v_mov_b32_e32 v93, v2
	v_mov_b32_e32 v94, v2
	v_mov_b32_e32 v95, v2
	v_mov_b32_e32 v96, v2
	v_mov_b32_e32 v97, v2
	v_mov_b32_e32 v106, v2
	v_mov_b32_e32 v107, v2
	v_mov_b32_e32 v108, v2
	v_mov_b32_e32 v109, v2
	v_mov_b32_e32 v110, v2
	v_mov_b32_e32 v111, v2
	v_mov_b32_e32 v112, v2
	v_mov_b32_e32 v113, v2
	v_mov_b32_e32 v122, v2
	v_mov_b32_e32 v123, v2
	v_mov_b32_e32 v124, v2
	v_mov_b32_e32 v125, v2
	v_mov_b32_e32 v126, v2
	v_mov_b32_e32 v127, v2
	v_mov_b32_e32 v128, v2
	v_mov_b32_e32 v129, v2
	v_mov_b32_e32 v138, v2
	v_mov_b32_e32 v139, v2
	v_mov_b32_e32 v140, v2
	v_mov_b32_e32 v141, v2
	v_mov_b32_e32 v142, v2
	v_mov_b32_e32 v143, v2
	v_mov_b32_e32 v144, v2
	v_mov_b32_e32 v145, v2
	v_add_u32_e32 v229, 0x10000, v159
.LBB0_1196:
	s_add_u32 s16, s14, 1
	s_addc_u32 s17, s15, 0
	s_lshl_b64 s[16:17], s[16:17], s60
	s_add_u32 s16, s12, s16
	s_addc_u32 s17, s13, s17
	s_cmp_eq_u32 s14, 31
	s_cselect_b32 s46, s42, s16
	s_cselect_b32 s47, s43, s17
	s_cselect_b32 s22, s44, s73
	s_cselect_b32 s23, s45, s74
	s_add_u32 s16, s46, s59
	s_addc_u32 s17, s47, 0
	s_add_i32 s75, 0, 0x10000
	s_add_i32 s78, 0, 0x14000
	ds_read_b128 v[66:69], v229
	ds_read_b128 v[70:73], v229 offset:1024
	ds_read_b128 v[74:77], v229 offset:2048
	ds_read_b128 v[78:81], v229 offset:3072
	ds_read_b128 v[164:167], v229 offset:16384
	ds_read_b128 v[168:171], v229 offset:17408
	ds_read_b128 v[172:175], v229 offset:18432
	ds_read_b128 v[176:179], v229 offset:19456
	s_lshl_b64 s[76:77], s[14:15], s60
	s_add_u32 s76, s31, s76
	s_addc_u32 s77, s41, s77
	s_add_i32 m0, s54, 0xc000
	ds_read_b128 v[180:183], v161
	ds_read_b128 v[184:187], v161 offset:1024
	ds_read_b128 v[188:191], v161 offset:2048
	ds_read_b128 v[192:195], v161 offset:3072
	ds_read_b128 v[196:199], v161 offset:4096
	ds_read_b128 v[200:203], v161 offset:5120
	ds_read_b128 v[204:207], v161 offset:6144
	ds_read_b128 v[212:215], v161 offset:7168
	global_load_lds_dwordx4 v152, s[76:77]
	s_add_i32 m0, s54, 0xe000
	s_nop 0
	global_load_lds_dwordx4 v150, s[76:77]
	s_waitcnt vmcnt(8)
	s_waitcnt lgkmcnt(0)
	s_barrier
	s_setprio 1
	s_waitcnt lgkmcnt(0)
	v_mfma_f32_16x16x32_bf16 v[142:145], v[66:69], v[180:183], v[142:145]
	v_mfma_f32_16x16x32_bf16 v[138:141], v[74:77], v[180:183], v[138:141]
	v_mfma_f32_16x16x32_bf16 v[126:129], v[66:69], v[188:191], v[126:129]
	v_mfma_f32_16x16x32_bf16 v[122:125], v[74:77], v[188:191], v[122:125]
	v_mfma_f32_16x16x32_bf16 v[110:113], v[66:69], v[196:199], v[110:113]
	v_mfma_f32_16x16x32_bf16 v[106:109], v[74:77], v[196:199], v[106:109]
	v_mfma_f32_16x16x32_bf16 v[94:97], v[66:69], v[204:207], v[94:97]
	v_mfma_f32_16x16x32_bf16 v[90:93], v[74:77], v[204:207], v[90:93]
	v_mfma_f32_16x16x32_bf16 v[142:145], v[70:73], v[184:187], v[142:145]
	v_mfma_f32_16x16x32_bf16 v[138:141], v[78:81], v[184:187], v[138:141]
	v_mfma_f32_16x16x32_bf16 v[126:129], v[70:73], v[192:195], v[126:129]
	v_mfma_f32_16x16x32_bf16 v[122:125], v[78:81], v[192:195], v[122:125]
	v_mfma_f32_16x16x32_bf16 v[110:113], v[70:73], v[200:203], v[110:113]
	v_mfma_f32_16x16x32_bf16 v[106:109], v[78:81], v[200:203], v[106:109]
	v_mfma_f32_16x16x32_bf16 v[94:97], v[70:73], v[212:215], v[94:97]
	v_mfma_f32_16x16x32_bf16 v[90:93], v[78:81], v[212:215], v[90:93]
	s_setprio 0
	s_setprio 1
	v_mfma_f32_16x16x32_bf16 v[134:137], v[164:167], v[180:183], v[134:137]
	v_mfma_f32_16x16x32_bf16 v[130:133], v[172:175], v[180:183], v[130:133]
	v_mfma_f32_16x16x32_bf16 v[118:121], v[164:167], v[188:191], v[118:121]
	v_mfma_f32_16x16x32_bf16 v[114:117], v[172:175], v[188:191], v[114:117]
	v_mfma_f32_16x16x32_bf16 v[102:105], v[164:167], v[196:199], v[102:105]
	v_mfma_f32_16x16x32_bf16 v[98:101], v[172:175], v[196:199], v[98:101]
	v_mfma_f32_16x16x32_bf16 v[86:89], v[164:167], v[204:207], v[86:89]
	v_mfma_f32_16x16x32_bf16 v[82:85], v[172:175], v[204:207], v[82:85]
	v_mfma_f32_16x16x32_bf16 v[134:137], v[168:171], v[184:187], v[134:137]
	v_mfma_f32_16x16x32_bf16 v[130:133], v[176:179], v[184:187], v[130:133]
	v_mfma_f32_16x16x32_bf16 v[118:121], v[168:171], v[192:195], v[118:121]
	v_mfma_f32_16x16x32_bf16 v[114:117], v[176:179], v[192:195], v[114:117]
	v_mfma_f32_16x16x32_bf16 v[102:105], v[168:171], v[200:203], v[102:105]
	v_mfma_f32_16x16x32_bf16 v[98:101], v[176:179], v[200:203], v[98:101]
	v_mfma_f32_16x16x32_bf16 v[86:89], v[168:171], v[212:215], v[86:89]
	v_mfma_f32_16x16x32_bf16 v[82:85], v[176:179], v[212:215], v[82:85]
	s_setprio 0
	s_barrier
	s_add_i32 s75, s75, s53
	s_mov_b32 m0, s75
	ds_read_b128 v[180:183], v161 offset:16384
	ds_read_b128 v[184:187], v161 offset:17408
	ds_read_b128 v[188:191], v161 offset:18432
	ds_read_b128 v[192:195], v161 offset:19456
	ds_read_b128 v[196:199], v161 offset:20480
	ds_read_b128 v[200:203], v161 offset:21504
	ds_read_b128 v[204:207], v161 offset:22528
	ds_read_b128 v[212:215], v161 offset:23552
	global_load_lds_dwordx4 v146, s[22:23]
	s_add_i32 m0, s75, 0x2000
	s_add_u32 s76, s22, 0x4000
	s_addc_u32 s77, s23, 0
	s_add_i32 s75, s78, s53
	global_load_lds_dwordx4 v148, s[22:23]
	s_mov_b32 m0, s75
	s_nop 0
	global_load_lds_dwordx4 v146, s[76:77]
	s_add_i32 m0, s75, 0x2000
	s_nop 0
	global_load_lds_dwordx4 v148, s[76:77]
	s_mov_b32 m0, s54
	s_nop 0
	global_load_lds_dwordx4 v152, s[46:47]
	s_mov_b32 m0, s55
	s_nop 0
	global_load_lds_dwordx4 v150, s[46:47]
	s_waitcnt vmcnt(8)
	s_waitcnt lgkmcnt(0)
	s_barrier
	s_setprio 1
	s_waitcnt lgkmcnt(0)
	v_mfma_f32_16x16x32_bf16 v[62:65], v[66:69], v[180:183], v[62:65]
	v_mfma_f32_16x16x32_bf16 v[58:61], v[74:77], v[180:183], v[58:61]
	v_mfma_f32_16x16x32_bf16 v[46:49], v[66:69], v[188:191], v[46:49]
	v_mfma_f32_16x16x32_bf16 v[42:45], v[74:77], v[188:191], v[42:45]
	v_mfma_f32_16x16x32_bf16 v[30:33], v[66:69], v[196:199], v[30:33]
	v_mfma_f32_16x16x32_bf16 v[26:29], v[74:77], v[196:199], v[26:29]
	v_mfma_f32_16x16x32_bf16 v[14:17], v[66:69], v[204:207], v[14:17]
	v_mfma_f32_16x16x32_bf16 v[10:13], v[74:77], v[204:207], v[10:13]
	v_mfma_f32_16x16x32_bf16 v[62:65], v[70:73], v[184:187], v[62:65]
	v_mfma_f32_16x16x32_bf16 v[58:61], v[78:81], v[184:187], v[58:61]
	v_mfma_f32_16x16x32_bf16 v[46:49], v[70:73], v[192:195], v[46:49]
	v_mfma_f32_16x16x32_bf16 v[42:45], v[78:81], v[192:195], v[42:45]
	v_mfma_f32_16x16x32_bf16 v[30:33], v[70:73], v[200:203], v[30:33]
	v_mfma_f32_16x16x32_bf16 v[26:29], v[78:81], v[200:203], v[26:29]
	v_mfma_f32_16x16x32_bf16 v[14:17], v[70:73], v[212:215], v[14:17]
	v_mfma_f32_16x16x32_bf16 v[10:13], v[78:81], v[212:215], v[10:13]
	s_setprio 0
	s_setprio 1
	v_mfma_f32_16x16x32_bf16 v[54:57], v[164:167], v[180:183], v[54:57]
	v_mfma_f32_16x16x32_bf16 v[50:53], v[172:175], v[180:183], v[50:53]
	v_mfma_f32_16x16x32_bf16 v[38:41], v[164:167], v[188:191], v[38:41]
	v_mfma_f32_16x16x32_bf16 v[34:37], v[172:175], v[188:191], v[34:37]
	v_mfma_f32_16x16x32_bf16 v[22:25], v[164:167], v[196:199], v[22:25]
	v_mfma_f32_16x16x32_bf16 v[18:21], v[172:175], v[196:199], v[18:21]
	v_mfma_f32_16x16x32_bf16 v[6:9], v[164:167], v[204:207], v[6:9]
	v_mfma_f32_16x16x32_bf16 v[2:5], v[172:175], v[204:207], v[2:5]
	v_mfma_f32_16x16x32_bf16 v[54:57], v[168:171], v[184:187], v[54:57]
	v_mfma_f32_16x16x32_bf16 v[50:53], v[176:179], v[184:187], v[50:53]
	v_mfma_f32_16x16x32_bf16 v[38:41], v[168:171], v[192:195], v[38:41]
	v_mfma_f32_16x16x32_bf16 v[34:37], v[176:179], v[192:195], v[34:37]
	v_mfma_f32_16x16x32_bf16 v[22:25], v[168:171], v[200:203], v[22:25]
	v_mfma_f32_16x16x32_bf16 v[18:21], v[176:179], v[200:203], v[18:21]
	v_mfma_f32_16x16x32_bf16 v[6:9], v[168:171], v[212:215], v[6:9]
	v_mfma_f32_16x16x32_bf16 v[2:5], v[176:179], v[212:215], v[2:5]
	s_setprio 0
	s_barrier
	s_add_i32 s75, 0, 0x18000
	s_add_i32 s76, 0, 0x1c000
	ds_read_b128 v[66:69], v229 offset:32768
	ds_read_b128 v[70:73], v229 offset:33792
	ds_read_b128 v[74:77], v229 offset:34816
	ds_read_b128 v[78:81], v229 offset:35840
	ds_read_b128 v[164:167], v229 offset:49152
	ds_read_b128 v[168:171], v229 offset:50176
	ds_read_b128 v[172:175], v229 offset:51200
	ds_read_b128 v[176:179], v229 offset:52224
	s_add_u32 s46, s46, s52
	s_addc_u32 s47, s47, 0
	s_mov_b32 m0, s56
	ds_read_b128 v[180:183], v161 offset:32768
	ds_read_b128 v[184:187], v161 offset:33792
	ds_read_b128 v[188:191], v161 offset:34816
	ds_read_b128 v[192:195], v161 offset:35840
	ds_read_b128 v[196:199], v161 offset:36864
	ds_read_b128 v[200:203], v161 offset:37888
	ds_read_b128 v[204:207], v161 offset:38912
	ds_read_b128 v[212:215], v161 offset:39936
	global_load_lds_dwordx4 v152, s[46:47]
	s_mov_b32 m0, s57
	s_nop 0
	global_load_lds_dwordx4 v150, s[46:47]
	s_waitcnt vmcnt(8)
	s_waitcnt lgkmcnt(0)
	s_barrier
	s_setprio 1
	s_waitcnt lgkmcnt(0)
	v_mfma_f32_16x16x32_bf16 v[142:145], v[66:69], v[180:183], v[142:145]
	v_mfma_f32_16x16x32_bf16 v[138:141], v[74:77], v[180:183], v[138:141]
	v_mfma_f32_16x16x32_bf16 v[126:129], v[66:69], v[188:191], v[126:129]
	v_mfma_f32_16x16x32_bf16 v[122:125], v[74:77], v[188:191], v[122:125]
	v_mfma_f32_16x16x32_bf16 v[110:113], v[66:69], v[196:199], v[110:113]
	v_mfma_f32_16x16x32_bf16 v[106:109], v[74:77], v[196:199], v[106:109]
	v_mfma_f32_16x16x32_bf16 v[94:97], v[66:69], v[204:207], v[94:97]
	v_mfma_f32_16x16x32_bf16 v[90:93], v[74:77], v[204:207], v[90:93]
	v_mfma_f32_16x16x32_bf16 v[142:145], v[70:73], v[184:187], v[142:145]
	v_mfma_f32_16x16x32_bf16 v[138:141], v[78:81], v[184:187], v[138:141]
	v_mfma_f32_16x16x32_bf16 v[126:129], v[70:73], v[192:195], v[126:129]
	v_mfma_f32_16x16x32_bf16 v[122:125], v[78:81], v[192:195], v[122:125]
	v_mfma_f32_16x16x32_bf16 v[110:113], v[70:73], v[200:203], v[110:113]
	v_mfma_f32_16x16x32_bf16 v[106:109], v[78:81], v[200:203], v[106:109]
	v_mfma_f32_16x16x32_bf16 v[94:97], v[70:73], v[212:215], v[94:97]
	v_mfma_f32_16x16x32_bf16 v[90:93], v[78:81], v[212:215], v[90:93]
	s_setprio 0
	s_setprio 1
	v_mfma_f32_16x16x32_bf16 v[134:137], v[164:167], v[180:183], v[134:137]
	v_mfma_f32_16x16x32_bf16 v[130:133], v[172:175], v[180:183], v[130:133]
	v_mfma_f32_16x16x32_bf16 v[118:121], v[164:167], v[188:191], v[118:121]
	v_mfma_f32_16x16x32_bf16 v[114:117], v[172:175], v[188:191], v[114:117]
	v_mfma_f32_16x16x32_bf16 v[102:105], v[164:167], v[196:199], v[102:105]
	v_mfma_f32_16x16x32_bf16 v[98:101], v[172:175], v[196:199], v[98:101]
	v_mfma_f32_16x16x32_bf16 v[86:89], v[164:167], v[204:207], v[86:89]
	v_mfma_f32_16x16x32_bf16 v[82:85], v[172:175], v[204:207], v[82:85]
	v_mfma_f32_16x16x32_bf16 v[134:137], v[168:171], v[184:187], v[134:137]
	v_mfma_f32_16x16x32_bf16 v[130:133], v[176:179], v[184:187], v[130:133]
	v_mfma_f32_16x16x32_bf16 v[118:121], v[168:171], v[192:195], v[118:121]
	v_mfma_f32_16x16x32_bf16 v[114:117], v[176:179], v[192:195], v[114:117]
	v_mfma_f32_16x16x32_bf16 v[102:105], v[168:171], v[200:203], v[102:105]
	v_mfma_f32_16x16x32_bf16 v[98:101], v[176:179], v[200:203], v[98:101]
	v_mfma_f32_16x16x32_bf16 v[86:89], v[168:171], v[212:215], v[86:89]
	v_mfma_f32_16x16x32_bf16 v[82:85], v[176:179], v[212:215], v[82:85]
	s_setprio 0
	s_barrier
	s_add_u32 s46, s22, 0x8000
	s_addc_u32 s47, s23, 0
	s_add_i32 s75, s75, s53
	s_mov_b32 m0, s75
	ds_read_b128 v[180:183], v161 offset:49152
	ds_read_b128 v[184:187], v161 offset:50176
	ds_read_b128 v[188:191], v161 offset:51200
	ds_read_b128 v[192:195], v161 offset:52224
	ds_read_b128 v[196:199], v161 offset:53248
	ds_read_b128 v[200:203], v161 offset:54272
	ds_read_b128 v[204:207], v161 offset:55296
	ds_read_b128 v[212:215], v161 offset:56320
	global_load_lds_dwordx4 v146, s[46:47]
	s_add_i32 m0, s75, 0x2000
	s_add_u32 s22, s22, 0xc000
	s_addc_u32 s23, s23, 0
	global_load_lds_dwordx4 v148, s[46:47]
	s_add_i32 s46, s76, s53
	s_mov_b32 m0, s46
	s_nop 0
	global_load_lds_dwordx4 v146, s[22:23]
	s_add_i32 m0, s46, 0x2000
	s_nop 0
	global_load_lds_dwordx4 v148, s[22:23]
	s_mov_b32 m0, s63
	s_nop 0
	global_load_lds_dwordx4 v152, s[16:17]
	s_mov_b32 m0, s64
	s_nop 0
	global_load_lds_dwordx4 v150, s[16:17]
	s_waitcnt vmcnt(8)
	s_waitcnt lgkmcnt(0)
	s_barrier
	s_setprio 1
	s_waitcnt lgkmcnt(0)
	v_mfma_f32_16x16x32_bf16 v[62:65], v[66:69], v[180:183], v[62:65]
	v_mfma_f32_16x16x32_bf16 v[58:61], v[74:77], v[180:183], v[58:61]
	v_mfma_f32_16x16x32_bf16 v[46:49], v[66:69], v[188:191], v[46:49]
	v_mfma_f32_16x16x32_bf16 v[42:45], v[74:77], v[188:191], v[42:45]
	v_mfma_f32_16x16x32_bf16 v[30:33], v[66:69], v[196:199], v[30:33]
	v_mfma_f32_16x16x32_bf16 v[26:29], v[74:77], v[196:199], v[26:29]
	v_mfma_f32_16x16x32_bf16 v[14:17], v[66:69], v[204:207], v[14:17]
	v_mfma_f32_16x16x32_bf16 v[10:13], v[74:77], v[204:207], v[10:13]
	v_mfma_f32_16x16x32_bf16 v[62:65], v[70:73], v[184:187], v[62:65]
	v_mfma_f32_16x16x32_bf16 v[58:61], v[78:81], v[184:187], v[58:61]
	v_mfma_f32_16x16x32_bf16 v[46:49], v[70:73], v[192:195], v[46:49]
	v_mfma_f32_16x16x32_bf16 v[42:45], v[78:81], v[192:195], v[42:45]
	v_mfma_f32_16x16x32_bf16 v[30:33], v[70:73], v[200:203], v[30:33]
	v_mfma_f32_16x16x32_bf16 v[26:29], v[78:81], v[200:203], v[26:29]
	v_mfma_f32_16x16x32_bf16 v[14:17], v[70:73], v[212:215], v[14:17]
	v_mfma_f32_16x16x32_bf16 v[10:13], v[78:81], v[212:215], v[10:13]
	s_setprio 0
	s_setprio 1
	v_mfma_f32_16x16x32_bf16 v[54:57], v[164:167], v[180:183], v[54:57]
	v_mfma_f32_16x16x32_bf16 v[50:53], v[172:175], v[180:183], v[50:53]
	v_mfma_f32_16x16x32_bf16 v[38:41], v[164:167], v[188:191], v[38:41]
	v_mfma_f32_16x16x32_bf16 v[34:37], v[172:175], v[188:191], v[34:37]
	v_mfma_f32_16x16x32_bf16 v[22:25], v[164:167], v[196:199], v[22:25]
	v_mfma_f32_16x16x32_bf16 v[18:21], v[172:175], v[196:199], v[18:21]
	v_mfma_f32_16x16x32_bf16 v[6:9], v[164:167], v[204:207], v[6:9]
	v_mfma_f32_16x16x32_bf16 v[2:5], v[172:175], v[204:207], v[2:5]
	v_mfma_f32_16x16x32_bf16 v[54:57], v[168:171], v[184:187], v[54:57]
	v_mfma_f32_16x16x32_bf16 v[50:53], v[176:179], v[184:187], v[50:53]
	v_mfma_f32_16x16x32_bf16 v[38:41], v[168:171], v[192:195], v[38:41]
	v_mfma_f32_16x16x32_bf16 v[34:37], v[176:179], v[192:195], v[34:37]
	v_mfma_f32_16x16x32_bf16 v[22:25], v[168:171], v[200:203], v[22:25]
	v_mfma_f32_16x16x32_bf16 v[18:21], v[176:179], v[200:203], v[18:21]
	v_mfma_f32_16x16x32_bf16 v[6:9], v[168:171], v[212:215], v[6:9]
	v_mfma_f32_16x16x32_bf16 v[2:5], v[176:179], v[212:215], v[2:5]
	s_setprio 0
	s_barrier
	s_add_u32 s14, s14, 2
	s_addc_u32 s15, s15, 0
	s_add_i32 s16, s14, -3
	s_add_u32 s73, s73, 0x10000
	s_addc_u32 s74, s74, 0
	s_cmp_gt_u32 s16, 29
	s_cbranch_scc0 .LBB0_1196
	s_and_b64 vcc, exec, s[26:27]
	s_cbranch_vccz .LBB0_1199
	s_barrier

.LBB0_1274:
	s_add_u32 s2, s4, 0xc000
	s_addc_u32 s3, s5, 0
	s_add_u32 s75, s12, 0x10000
	v_mov_b32_e32 v2, 0
	s_addc_u32 s76, s13, 0
	s_mov_b32 s77, -2
	v_mov_b32_e32 v3, v2
	v_mov_b32_e32 v4, v2
	v_mov_b32_e32 v5, v2
	v_mov_b32_e32 v6, v2
	v_mov_b32_e32 v7, v2
	s_waitcnt vmcnt(0)
	v_mov_b32_e32 v8, v2
	v_mov_b32_e32 v9, v2
	v_mov_b32_e32 v18, v2
	v_mov_b32_e32 v19, v2
	v_mov_b32_e32 v20, v2
	v_mov_b32_e32 v21, v2
	v_mov_b32_e32 v22, v2
	v_mov_b32_e32 v23, v2
	v_mov_b32_e32 v24, v2
	v_mov_b32_e32 v25, v2
	v_mov_b32_e32 v34, v2
	v_mov_b32_e32 v35, v2
	v_mov_b32_e32 v36, v2
	v_mov_b32_e32 v37, v2
	v_mov_b32_e32 v38, v2
	v_mov_b32_e32 v39, v2
	v_mov_b32_e32 v40, v2
	v_mov_b32_e32 v41, v2
	v_mov_b32_e32 v50, v2
	v_mov_b32_e32 v51, v2
	v_mov_b32_e32 v52, v2
	v_mov_b32_e32 v53, v2
	v_mov_b32_e32 v54, v2
	v_mov_b32_e32 v55, v2
	v_mov_b32_e32 v56, v2
	v_mov_b32_e32 v57, v2
	v_mov_b32_e32 v10, v2
	v_mov_b32_e32 v11, v2
	v_mov_b32_e32 v12, v2
	v_mov_b32_e32 v13, v2
	v_mov_b32_e32 v14, v2
	v_mov_b32_e32 v15, v2
	v_mov_b32_e32 v16, v2
	v_mov_b32_e32 v17, v2
	v_mov_b32_e32 v26, v2
	v_mov_b32_e32 v27, v2
	v_mov_b32_e32 v28, v2
	v_mov_b32_e32 v29, v2
	v_mov_b32_e32 v30, v2
	v_mov_b32_e32 v31, v2
	v_mov_b32_e32 v32, v2
	v_mov_b32_e32 v33, v2
	v_mov_b32_e32 v42, v2
	v_mov_b32_e32 v43, v2
	v_mov_b32_e32 v44, v2
	v_mov_b32_e32 v45, v2
	v_mov_b32_e32 v46, v2
	v_mov_b32_e32 v47, v2
	v_mov_b32_e32 v48, v2
	v_mov_b32_e32 v49, v2
	v_mov_b32_e32 v74, v2
	v_mov_b32_e32 v75, v2
	v_mov_b32_e32 v76, v2
	v_mov_b32_e32 v77, v2
	v_mov_b32_e32 v78, v2
	v_mov_b32_e32 v79, v2
	v_mov_b32_e32 v80, v2
	v_mov_b32_e32 v81, v2
	v_mov_b32_e32 v82, v2
	v_mov_b32_e32 v83, v2
	v_mov_b32_e32 v84, v2
	v_mov_b32_e32 v85, v2
	v_mov_b32_e32 v86, v2
	v_mov_b32_e32 v87, v2
	v_mov_b32_e32 v88, v2
	v_mov_b32_e32 v89, v2
	v_mov_b32_e32 v98, v2
	v_mov_b32_e32 v99, v2
	v_mov_b32_e32 v100, v2
	v_mov_b32_e32 v101, v2
	v_mov_b32_e32 v102, v2
	v_mov_b32_e32 v103, v2
	v_mov_b32_e32 v104, v2
	v_mov_b32_e32 v105, v2
	v_mov_b32_e32 v114, v2
	v_mov_b32_e32 v115, v2
	v_mov_b32_e32 v116, v2
	v_mov_b32_e32 v117, v2
	v_mov_b32_e32 v118, v2
	v_mov_b32_e32 v119, v2
	v_mov_b32_e32 v120, v2
	v_mov_b32_e32 v121, v2
	v_mov_b32_e32 v130, v2
	v_mov_b32_e32 v131, v2
	v_mov_b32_e32 v132, v2
	v_mov_b32_e32 v133, v2
	v_mov_b32_e32 v134, v2
	v_mov_b32_e32 v135, v2
	v_mov_b32_e32 v136, v2
	v_mov_b32_e32 v137, v2
	v_mov_b32_e32 v90, v2
	v_mov_b32_e32 v91, v2
	v_mov_b32_e32 v92, v2
	v_mov_b32_e32 v93, v2
	v_mov_b32_e32 v94, v2
	v_mov_b32_e32 v95, v2
	v_mov_b32_e32 v96, v2
	v_mov_b32_e32 v97, v2
	v_mov_b32_e32 v106, v2
	v_mov_b32_e32 v107, v2
	v_mov_b32_e32 v108, v2
	v_mov_b32_e32 v109, v2
	v_mov_b32_e32 v110, v2
	v_mov_b32_e32 v111, v2
	v_mov_b32_e32 v112, v2
	v_mov_b32_e32 v113, v2
	v_mov_b32_e32 v122, v2
	v_mov_b32_e32 v123, v2
	v_mov_b32_e32 v124, v2
	v_mov_b32_e32 v125, v2
	v_mov_b32_e32 v126, v2
	v_mov_b32_e32 v127, v2
	v_mov_b32_e32 v128, v2
	v_mov_b32_e32 v129, v2
	v_mov_b32_e32 v138, v2
	v_mov_b32_e32 v139, v2
	v_mov_b32_e32 v140, v2
	v_mov_b32_e32 v141, v2
	v_mov_b32_e32 v142, v2
	v_mov_b32_e32 v143, v2
	v_mov_b32_e32 v144, v2
	v_mov_b32_e32 v145, v2
	v_add_u32_e32 v229, 0x10000, v224
.LBB0_1275:
	s_add_u32 s4, s2, 0x4000
	s_addc_u32 s5, s3, 0
	s_cmpk_eq_i32 s77, 0x52
	s_cselect_b32 s14, s54, s4
	s_cselect_b32 s15, s55, s5
	s_cselect_b32 s12, s56, s75
	s_cselect_b32 s13, s57, s76
	s_add_u32 s4, s14, 0x8000
	s_addc_u32 s5, s15, 0
	s_add_i32 s78, 0, 0x10000
	s_add_i32 s80, 0, 0x14000
	ds_read_b128 v[58:61], v229
	ds_read_b128 v[62:65], v229 offset:1024
	ds_read_b128 v[66:69], v229 offset:2048
	ds_read_b128 v[70:73], v229 offset:3072
	ds_read_b128 v[146:149], v229 offset:16384
	ds_read_b128 v[150:153], v229 offset:17408
	ds_read_b128 v[154:157], v229 offset:18432
	ds_read_b128 v[158:161], v229 offset:19456
	s_add_i32 m0, s59, 0xc000
	ds_read_b128 v[162:165], v225
	ds_read_b128 v[166:169], v225 offset:1024
	ds_read_b128 v[170:173], v225 offset:2048
	ds_read_b128 v[174:177], v225 offset:3072
	ds_read_b128 v[178:181], v225 offset:4096
	ds_read_b128 v[182:185], v225 offset:5120
	ds_read_b128 v[192:195], v225 offset:6144
	ds_read_b128 v[196:199], v225 offset:7168
	global_load_lds_dwordx4 v186, s[2:3]
	s_add_i32 m0, s59, 0xe000
	s_nop 0
	global_load_lds_dwordx4 v188, s[2:3]
	s_waitcnt vmcnt(8)
	s_waitcnt lgkmcnt(0)
	s_barrier
	s_setprio 1
	s_waitcnt lgkmcnt(0)
	v_mfma_f32_16x16x32_bf16 v[142:145], v[58:61], v[162:165], v[142:145]
	v_mfma_f32_16x16x32_bf16 v[138:141], v[66:69], v[162:165], v[138:141]
	v_mfma_f32_16x16x32_bf16 v[126:129], v[58:61], v[170:173], v[126:129]
	v_mfma_f32_16x16x32_bf16 v[122:125], v[66:69], v[170:173], v[122:125]
	v_mfma_f32_16x16x32_bf16 v[110:113], v[58:61], v[178:181], v[110:113]
	v_mfma_f32_16x16x32_bf16 v[106:109], v[66:69], v[178:181], v[106:109]
	v_mfma_f32_16x16x32_bf16 v[94:97], v[58:61], v[192:195], v[94:97]
	v_mfma_f32_16x16x32_bf16 v[90:93], v[66:69], v[192:195], v[90:93]
	v_mfma_f32_16x16x32_bf16 v[142:145], v[62:65], v[166:169], v[142:145]
	v_mfma_f32_16x16x32_bf16 v[138:141], v[70:73], v[166:169], v[138:141]
	v_mfma_f32_16x16x32_bf16 v[126:129], v[62:65], v[174:177], v[126:129]
	v_mfma_f32_16x16x32_bf16 v[122:125], v[70:73], v[174:177], v[122:125]
	v_mfma_f32_16x16x32_bf16 v[110:113], v[62:65], v[182:185], v[110:113]
	v_mfma_f32_16x16x32_bf16 v[106:109], v[70:73], v[182:185], v[106:109]
	v_mfma_f32_16x16x32_bf16 v[94:97], v[62:65], v[196:199], v[94:97]
	v_mfma_f32_16x16x32_bf16 v[90:93], v[70:73], v[196:199], v[90:93]
	s_setprio 0
	s_setprio 1
	v_mfma_f32_16x16x32_bf16 v[134:137], v[146:149], v[162:165], v[134:137]
	v_mfma_f32_16x16x32_bf16 v[130:133], v[154:157], v[162:165], v[130:133]
	v_mfma_f32_16x16x32_bf16 v[118:121], v[146:149], v[170:173], v[118:121]
	v_mfma_f32_16x16x32_bf16 v[114:117], v[154:157], v[170:173], v[114:117]
	v_mfma_f32_16x16x32_bf16 v[102:105], v[146:149], v[178:181], v[102:105]
	v_mfma_f32_16x16x32_bf16 v[98:101], v[154:157], v[178:181], v[98:101]
	v_mfma_f32_16x16x32_bf16 v[86:89], v[146:149], v[192:195], v[86:89]
	v_mfma_f32_16x16x32_bf16 v[82:85], v[154:157], v[192:195], v[82:85]
	v_mfma_f32_16x16x32_bf16 v[134:137], v[150:153], v[166:169], v[134:137]
	v_mfma_f32_16x16x32_bf16 v[130:133], v[158:161], v[166:169], v[130:133]
	v_mfma_f32_16x16x32_bf16 v[118:121], v[150:153], v[174:177], v[118:121]
	v_mfma_f32_16x16x32_bf16 v[114:117], v[158:161], v[174:177], v[114:117]
	v_mfma_f32_16x16x32_bf16 v[102:105], v[150:153], v[182:185], v[102:105]
	v_mfma_f32_16x16x32_bf16 v[98:101], v[158:161], v[182:185], v[98:101]
	v_mfma_f32_16x16x32_bf16 v[86:89], v[150:153], v[196:199], v[86:89]
	v_mfma_f32_16x16x32_bf16 v[82:85], v[158:161], v[196:199], v[82:85]
	s_setprio 0
	s_barrier
	s_add_i32 s78, s78, s58
	s_mov_b32 m0, s78
	ds_read_b128 v[162:165], v225 offset:16384
	ds_read_b128 v[166:169], v225 offset:17408
	ds_read_b128 v[170:173], v225 offset:18432
	ds_read_b128 v[174:177], v225 offset:19456
	ds_read_b128 v[178:181], v225 offset:20480
	ds_read_b128 v[182:185], v225 offset:21504
	ds_read_b128 v[192:195], v225 offset:22528
	ds_read_b128 v[196:199], v225 offset:23552
	global_load_lds_dwordx4 v186, s[12:13]
	s_add_i32 m0, s78, 0x2000
	s_add_u32 s78, s12, 0x4000
	s_addc_u32 s79, s13, 0
	s_add_i32 s80, s80, s58
	global_load_lds_dwordx4 v188, s[12:13]
	s_mov_b32 m0, s80
	s_nop 0
	global_load_lds_dwordx4 v186, s[78:79]
	s_add_i32 m0, s80, 0x2000
	s_nop 0
	global_load_lds_dwordx4 v188, s[78:79]
	s_mov_b32 m0, s59
	s_nop 0
	global_load_lds_dwordx4 v186, s[14:15]
	s_mov_b32 m0, s60
	s_nop 0
	global_load_lds_dwordx4 v188, s[14:15]
	s_waitcnt vmcnt(8)
	s_waitcnt lgkmcnt(0)
	s_barrier
	s_setprio 1
	s_waitcnt lgkmcnt(0)
	v_mfma_f32_16x16x32_bf16 v[78:81], v[58:61], v[162:165], v[78:81]
	v_mfma_f32_16x16x32_bf16 v[74:77], v[66:69], v[162:165], v[74:77]
	v_mfma_f32_16x16x32_bf16 v[46:49], v[58:61], v[170:173], v[46:49]
	v_mfma_f32_16x16x32_bf16 v[42:45], v[66:69], v[170:173], v[42:45]
	v_mfma_f32_16x16x32_bf16 v[30:33], v[58:61], v[178:181], v[30:33]
	v_mfma_f32_16x16x32_bf16 v[26:29], v[66:69], v[178:181], v[26:29]
	v_mfma_f32_16x16x32_bf16 v[14:17], v[58:61], v[192:195], v[14:17]
	v_mfma_f32_16x16x32_bf16 v[10:13], v[66:69], v[192:195], v[10:13]
	v_mfma_f32_16x16x32_bf16 v[78:81], v[62:65], v[166:169], v[78:81]
	v_mfma_f32_16x16x32_bf16 v[74:77], v[70:73], v[166:169], v[74:77]
	v_mfma_f32_16x16x32_bf16 v[46:49], v[62:65], v[174:177], v[46:49]
	v_mfma_f32_16x16x32_bf16 v[42:45], v[70:73], v[174:177], v[42:45]
	v_mfma_f32_16x16x32_bf16 v[30:33], v[62:65], v[182:185], v[30:33]
	v_mfma_f32_16x16x32_bf16 v[26:29], v[70:73], v[182:185], v[26:29]
	v_mfma_f32_16x16x32_bf16 v[14:17], v[62:65], v[196:199], v[14:17]
	v_mfma_f32_16x16x32_bf16 v[10:13], v[70:73], v[196:199], v[10:13]
	s_setprio 0
	s_setprio 1
	v_mfma_f32_16x16x32_bf16 v[54:57], v[146:149], v[162:165], v[54:57]
	v_mfma_f32_16x16x32_bf16 v[50:53], v[154:157], v[162:165], v[50:53]
	v_mfma_f32_16x16x32_bf16 v[38:41], v[146:149], v[170:173], v[38:41]
	v_mfma_f32_16x16x32_bf16 v[34:37], v[154:157], v[170:173], v[34:37]
	v_mfma_f32_16x16x32_bf16 v[22:25], v[146:149], v[178:181], v[22:25]
	v_mfma_f32_16x16x32_bf16 v[18:21], v[154:157], v[178:181], v[18:21]
	v_mfma_f32_16x16x32_bf16 v[6:9], v[146:149], v[192:195], v[6:9]
	v_mfma_f32_16x16x32_bf16 v[2:5], v[154:157], v[192:195], v[2:5]
	v_mfma_f32_16x16x32_bf16 v[54:57], v[150:153], v[166:169], v[54:57]
	v_mfma_f32_16x16x32_bf16 v[50:53], v[158:161], v[166:169], v[50:53]
	v_mfma_f32_16x16x32_bf16 v[38:41], v[150:153], v[174:177], v[38:41]
	v_mfma_f32_16x16x32_bf16 v[34:37], v[158:161], v[174:177], v[34:37]
	v_mfma_f32_16x16x32_bf16 v[22:25], v[150:153], v[182:185], v[22:25]
	v_mfma_f32_16x16x32_bf16 v[18:21], v[158:161], v[182:185], v[18:21]
	v_mfma_f32_16x16x32_bf16 v[6:9], v[150:153], v[196:199], v[6:9]
	v_mfma_f32_16x16x32_bf16 v[2:5], v[158:161], v[196:199], v[2:5]
	s_setprio 0
	s_barrier
	s_add_i32 s78, 0, 0x18000
	s_add_i32 s79, 0, 0x1c000
	ds_read_b128 v[58:61], v229 offset:32768
	ds_read_b128 v[62:65], v229 offset:33792
	ds_read_b128 v[66:69], v229 offset:34816
	ds_read_b128 v[70:73], v229 offset:35840
	ds_read_b128 v[146:149], v229 offset:49152
	ds_read_b128 v[150:153], v229 offset:50176
	ds_read_b128 v[154:157], v229 offset:51200
	ds_read_b128 v[158:161], v229 offset:52224
	s_add_u32 s14, s14, 0x4000
	s_addc_u32 s15, s15, 0
	s_mov_b32 m0, s61
	ds_read_b128 v[162:165], v225 offset:32768
	ds_read_b128 v[166:169], v225 offset:33792
	ds_read_b128 v[170:173], v225 offset:34816
	ds_read_b128 v[174:177], v225 offset:35840
	ds_read_b128 v[178:181], v225 offset:36864
	ds_read_b128 v[182:185], v225 offset:37888
	ds_read_b128 v[192:195], v225 offset:38912
	ds_read_b128 v[196:199], v225 offset:39936
	global_load_lds_dwordx4 v186, s[14:15]
	s_mov_b32 m0, s62
	s_nop 0
	global_load_lds_dwordx4 v188, s[14:15]
	s_waitcnt vmcnt(8)
	s_waitcnt lgkmcnt(0)
	s_barrier
	s_setprio 1
	s_waitcnt lgkmcnt(0)
	v_mfma_f32_16x16x32_bf16 v[142:145], v[58:61], v[162:165], v[142:145]
	v_mfma_f32_16x16x32_bf16 v[138:141], v[66:69], v[162:165], v[138:141]
	v_mfma_f32_16x16x32_bf16 v[126:129], v[58:61], v[170:173], v[126:129]
	v_mfma_f32_16x16x32_bf16 v[122:125], v[66:69], v[170:173], v[122:125]
	v_mfma_f32_16x16x32_bf16 v[110:113], v[58:61], v[178:181], v[110:113]
	v_mfma_f32_16x16x32_bf16 v[106:109], v[66:69], v[178:181], v[106:109]
	v_mfma_f32_16x16x32_bf16 v[94:97], v[58:61], v[192:195], v[94:97]
	v_mfma_f32_16x16x32_bf16 v[90:93], v[66:69], v[192:195], v[90:93]
	v_mfma_f32_16x16x32_bf16 v[142:145], v[62:65], v[166:169], v[142:145]
	v_mfma_f32_16x16x32_bf16 v[138:141], v[70:73], v[166:169], v[138:141]
	v_mfma_f32_16x16x32_bf16 v[126:129], v[62:65], v[174:177], v[126:129]
	v_mfma_f32_16x16x32_bf16 v[122:125], v[70:73], v[174:177], v[122:125]
	v_mfma_f32_16x16x32_bf16 v[110:113], v[62:65], v[182:185], v[110:113]
	v_mfma_f32_16x16x32_bf16 v[106:109], v[70:73], v[182:185], v[106:109]
	v_mfma_f32_16x16x32_bf16 v[94:97], v[62:65], v[196:199], v[94:97]
	v_mfma_f32_16x16x32_bf16 v[90:93], v[70:73], v[196:199], v[90:93]
	s_setprio 0
	s_setprio 1
	v_mfma_f32_16x16x32_bf16 v[134:137], v[146:149], v[162:165], v[134:137]
	v_mfma_f32_16x16x32_bf16 v[130:133], v[154:157], v[162:165], v[130:133]
	v_mfma_f32_16x16x32_bf16 v[118:121], v[146:149], v[170:173], v[118:121]
	v_mfma_f32_16x16x32_bf16 v[114:117], v[154:157], v[170:173], v[114:117]
	v_mfma_f32_16x16x32_bf16 v[102:105], v[146:149], v[178:181], v[102:105]
	v_mfma_f32_16x16x32_bf16 v[98:101], v[154:157], v[178:181], v[98:101]
	v_mfma_f32_16x16x32_bf16 v[86:89], v[146:149], v[192:195], v[86:89]
	v_mfma_f32_16x16x32_bf16 v[82:85], v[154:157], v[192:195], v[82:85]
	v_mfma_f32_16x16x32_bf16 v[134:137], v[150:153], v[166:169], v[134:137]
	v_mfma_f32_16x16x32_bf16 v[130:133], v[158:161], v[166:169], v[130:133]
	v_mfma_f32_16x16x32_bf16 v[118:121], v[150:153], v[174:177], v[118:121]
	v_mfma_f32_16x16x32_bf16 v[114:117], v[158:161], v[174:177], v[114:117]
	v_mfma_f32_16x16x32_bf16 v[102:105], v[150:153], v[182:185], v[102:105]
	v_mfma_f32_16x16x32_bf16 v[98:101], v[158:161], v[182:185], v[98:101]
	v_mfma_f32_16x16x32_bf16 v[86:89], v[150:153], v[196:199], v[86:89]
	v_mfma_f32_16x16x32_bf16 v[82:85], v[158:161], v[196:199], v[82:85]
	s_setprio 0
	s_barrier
	s_add_u32 s14, s12, 0x8000
	s_addc_u32 s15, s13, 0
	s_add_i32 s78, s78, s58
	s_mov_b32 m0, s78
	ds_read_b128 v[162:165], v225 offset:49152
	ds_read_b128 v[166:169], v225 offset:50176
	ds_read_b128 v[170:173], v225 offset:51200
	ds_read_b128 v[174:177], v225 offset:52224
	ds_read_b128 v[178:181], v225 offset:53248
	ds_read_b128 v[182:185], v225 offset:54272
	ds_read_b128 v[192:195], v225 offset:55296
	ds_read_b128 v[196:199], v225 offset:56320
	global_load_lds_dwordx4 v186, s[14:15]
	s_add_i32 m0, s78, 0x2000
	s_add_u32 s12, s12, 0xc000
	s_addc_u32 s13, s13, 0
	global_load_lds_dwordx4 v188, s[14:15]
	s_add_i32 s14, s79, s58
	s_mov_b32 m0, s14
	s_nop 0
	global_load_lds_dwordx4 v186, s[12:13]
	s_add_i32 m0, s14, 0x2000
	s_nop 0
	global_load_lds_dwordx4 v188, s[12:13]
	s_mov_b32 m0, s65
	s_nop 0
	global_load_lds_dwordx4 v186, s[4:5]
	s_mov_b32 m0, s66
	s_nop 0
	global_load_lds_dwordx4 v188, s[4:5]
	s_waitcnt vmcnt(8)
	s_waitcnt lgkmcnt(0)
	s_barrier
	s_setprio 1
	s_waitcnt lgkmcnt(0)
	v_mfma_f32_16x16x32_bf16 v[78:81], v[58:61], v[162:165], v[78:81]
	v_mfma_f32_16x16x32_bf16 v[74:77], v[66:69], v[162:165], v[74:77]
	v_mfma_f32_16x16x32_bf16 v[46:49], v[58:61], v[170:173], v[46:49]
	v_mfma_f32_16x16x32_bf16 v[42:45], v[66:69], v[170:173], v[42:45]
	v_mfma_f32_16x16x32_bf16 v[30:33], v[58:61], v[178:181], v[30:33]
	v_mfma_f32_16x16x32_bf16 v[26:29], v[66:69], v[178:181], v[26:29]
	v_mfma_f32_16x16x32_bf16 v[14:17], v[58:61], v[192:195], v[14:17]
	v_mfma_f32_16x16x32_bf16 v[10:13], v[66:69], v[192:195], v[10:13]
	v_mfma_f32_16x16x32_bf16 v[78:81], v[62:65], v[166:169], v[78:81]
	v_mfma_f32_16x16x32_bf16 v[74:77], v[70:73], v[166:169], v[74:77]
	v_mfma_f32_16x16x32_bf16 v[46:49], v[62:65], v[174:177], v[46:49]
	v_mfma_f32_16x16x32_bf16 v[42:45], v[70:73], v[174:177], v[42:45]
	v_mfma_f32_16x16x32_bf16 v[30:33], v[62:65], v[182:185], v[30:33]
	v_mfma_f32_16x16x32_bf16 v[26:29], v[70:73], v[182:185], v[26:29]
	v_mfma_f32_16x16x32_bf16 v[14:17], v[62:65], v[196:199], v[14:17]
	v_mfma_f32_16x16x32_bf16 v[10:13], v[70:73], v[196:199], v[10:13]
	s_setprio 0
	s_setprio 1
	v_mfma_f32_16x16x32_bf16 v[54:57], v[146:149], v[162:165], v[54:57]
	v_mfma_f32_16x16x32_bf16 v[50:53], v[154:157], v[162:165], v[50:53]
	v_mfma_f32_16x16x32_bf16 v[38:41], v[146:149], v[170:173], v[38:41]
	v_mfma_f32_16x16x32_bf16 v[34:37], v[154:157], v[170:173], v[34:37]
	v_mfma_f32_16x16x32_bf16 v[22:25], v[146:149], v[178:181], v[22:25]
	v_mfma_f32_16x16x32_bf16 v[18:21], v[154:157], v[178:181], v[18:21]
	v_mfma_f32_16x16x32_bf16 v[6:9], v[146:149], v[192:195], v[6:9]
	v_mfma_f32_16x16x32_bf16 v[2:5], v[154:157], v[192:195], v[2:5]
	v_mfma_f32_16x16x32_bf16 v[54:57], v[150:153], v[166:169], v[54:57]
	v_mfma_f32_16x16x32_bf16 v[50:53], v[158:161], v[166:169], v[50:53]
	v_mfma_f32_16x16x32_bf16 v[38:41], v[150:153], v[174:177], v[38:41]
	v_mfma_f32_16x16x32_bf16 v[34:37], v[158:161], v[174:177], v[34:37]
	v_mfma_f32_16x16x32_bf16 v[22:25], v[150:153], v[182:185], v[22:25]
	v_mfma_f32_16x16x32_bf16 v[18:21], v[158:161], v[182:185], v[18:21]
	v_mfma_f32_16x16x32_bf16 v[6:9], v[150:153], v[196:199], v[6:9]
	v_mfma_f32_16x16x32_bf16 v[2:5], v[158:161], v[196:199], v[2:5]
	s_setprio 0
	s_barrier
	s_add_i32 s77, s77, 2
	s_add_u32 s2, s2, 0x10000
	s_addc_u32 s3, s3, 0
	s_add_u32 s75, s75, 0x10000
	s_addc_u32 s76, s76, 0
	s_cmpk_gt_u32 s77, 0x53
	s_cbranch_scc0 .LBB0_1275
	s_and_b64 vcc, exec, s[48:49]
	s_cbranch_vccz .LBB0_1278
	s_barrier
